# early closing barrier: 3 tail MFMAs after the segment's closing barrier, issued at s_setprio 3 so they are not starved by the partner's segment
# baseline (speedup 1.0000x reference)
.LBB0_200:
	ds_read_b128 v[148:151], v169
	ds_read_b128 v[152:155], v169 offset:1024
	ds_read_b128 v[156:159], v169 offset:2048
	ds_read_b128 v[160:163], v169 offset:3072
	ds_read_b128 v[174:177], v170
	ds_read_b128 v[178:181], v170 offset:1024
	ds_read_b128 v[182:185], v170 offset:2048
	ds_read_b128 v[186:189], v170 offset:3072
	s_add_u32 s26, s6, 0xfff00800
	s_addc_u32 s27, s7, -1
	s_cmp_eq_u32 s34, 60
	s_cselect_b32 s29, s17, s27
	s_cselect_b32 s28, s23, s26
	s_cselect_b32 s27, s15, s31
	s_cselect_b32 s26, s25, s30
	v_lshl_add_u64 v[190:191], s[6:7], 0, v[138:139]
	s_add_i32 m0, s41, 0xc000
	s_nop 0
	global_load_lds_dwordx4 v[190:191], off
	v_lshl_add_u64 v[190:191], s[6:7], 0, v[140:141]
	s_add_i32 m0, s41, 0xe000
	s_nop 0
	global_load_lds_dwordx4 v[190:191], off
	ds_read_b128 v[190:193], v171
	ds_read_b128 v[194:197], v171 offset:1024
	ds_read_b128 v[198:201], v171 offset:2048
	ds_read_b128 v[202:205], v171 offset:3072
	ds_read_b128 v[206:209], v171 offset:4096
	ds_read_b128 v[210:213], v171 offset:5120
	ds_read_b128 v[214:217], v171 offset:6144
	ds_read_b128 v[218:221], v171 offset:7168
	s_waitcnt vmcnt(8)
	s_waitcnt lgkmcnt(0)
	s_barrier
	v_mfma_f32_16x16x32_bf16 v[124:127], v[148:151], v[190:193], v[124:127]
	v_mfma_f32_16x16x32_bf16 v[124:127], v[152:155], v[194:197], v[124:127]
	v_mfma_f32_16x16x32_bf16 v[120:123], v[160:163], v[194:197], v[120:123]
	v_mfma_f32_16x16x32_bf16 v[120:123], v[156:159], v[190:193], v[120:123]
	v_mfma_f32_16x16x32_bf16 v[60:63], v[174:177], v[190:193], v[60:63]
	v_mfma_f32_16x16x32_bf16 v[60:63], v[178:181], v[194:197], v[60:63]
	v_mfma_f32_16x16x32_bf16 v[56:59], v[186:189], v[194:197], v[56:59]
	v_mfma_f32_16x16x32_bf16 v[56:59], v[182:185], v[190:193], v[56:59]
	v_mfma_f32_16x16x32_bf16 v[48:51], v[182:185], v[198:201], v[48:51]
	v_mfma_f32_16x16x32_bf16 v[48:51], v[186:189], v[202:205], v[48:51]
	v_mfma_f32_16x16x32_bf16 v[52:55], v[178:181], v[202:205], v[52:55]
	v_mfma_f32_16x16x32_bf16 v[52:55], v[174:177], v[198:201], v[52:55]
	v_mfma_f32_16x16x32_bf16 v[112:115], v[156:159], v[198:201], v[112:115]
	v_mfma_f32_16x16x32_bf16 v[112:115], v[160:163], v[202:205], v[112:115]
	v_mfma_f32_16x16x32_bf16 v[116:119], v[152:155], v[202:205], v[116:119]
	v_mfma_f32_16x16x32_bf16 v[116:119], v[148:151], v[198:201], v[116:119]
	v_mfma_f32_16x16x32_bf16 v[108:111], v[148:151], v[206:209], v[108:111]
	v_mfma_f32_16x16x32_bf16 v[108:111], v[152:155], v[210:213], v[108:111]
	v_mfma_f32_16x16x32_bf16 v[104:107], v[160:163], v[210:213], v[104:107]
	v_mfma_f32_16x16x32_bf16 v[104:107], v[156:159], v[206:209], v[104:107]
	v_mfma_f32_16x16x32_bf16 v[44:47], v[174:177], v[206:209], v[44:47]
	v_mfma_f32_16x16x32_bf16 v[44:47], v[178:181], v[210:213], v[44:47]
	v_mfma_f32_16x16x32_bf16 v[40:43], v[186:189], v[210:213], v[40:43]
	v_mfma_f32_16x16x32_bf16 v[40:43], v[182:185], v[206:209], v[40:43]
	v_mfma_f32_16x16x32_bf16 v[32:35], v[182:185], v[214:217], v[32:35]
	v_mfma_f32_16x16x32_bf16 v[32:35], v[186:189], v[218:221], v[32:35]
	v_mfma_f32_16x16x32_bf16 v[36:39], v[178:181], v[218:221], v[36:39]
	v_mfma_f32_16x16x32_bf16 v[36:39], v[174:177], v[214:217], v[36:39]
	v_mfma_f32_16x16x32_bf16 v[96:99], v[156:159], v[214:217], v[96:99]
	s_barrier
	s_setprio 3
	v_mfma_f32_16x16x32_bf16 v[96:99], v[160:163], v[218:221], v[96:99]
	v_mfma_f32_16x16x32_bf16 v[100:103], v[152:155], v[218:221], v[100:103]
	v_mfma_f32_16x16x32_bf16 v[100:103], v[148:151], v[214:217], v[100:103]
	s_setprio 0
	s_add_i32 s35, s55, s36
	v_lshl_add_u64 v[222:223], s[26:27], 0, v[130:131]
	s_mov_b32 m0, s35
	v_lshl_add_u64 v[224:225], s[26:27], 0, v[134:135]
	global_load_lds_dwordx4 v[222:223], off
	s_add_i32 m0, s35, 0x2000
	s_add_u32 s58, s26, 0x100000
	s_addc_u32 s59, s27, 0
	s_add_i32 s35, s56, s36
	global_load_lds_dwordx4 v[224:225], off
	v_lshl_add_u64 v[190:191], s[58:59], 0, v[130:131]
	s_mov_b32 m0, s35
	v_lshl_add_u64 v[226:227], s[28:29], 0, v[128:129]
	global_load_lds_dwordx4 v[190:191], off
	v_lshl_add_u64 v[190:191], s[58:59], 0, v[134:135]
	s_add_i32 m0, s35, 0x2000
	v_lshl_add_u64 v[228:229], s[28:29], 0, v[132:133]
	global_load_lds_dwordx4 v[190:191], off
	s_mov_b32 m0, s41
	s_nop 0
	global_load_lds_dwordx4 v[226:227], off
	s_mov_b32 m0, s42
	s_nop 0
	global_load_lds_dwordx4 v[228:229], off
	ds_read_b128 v[190:193], v171 offset:16384
	ds_read_b128 v[194:197], v171 offset:17408
	ds_read_b128 v[198:201], v171 offset:18432
	ds_read_b128 v[202:205], v171 offset:19456
	ds_read_b128 v[206:209], v171 offset:20480
	ds_read_b128 v[210:213], v171 offset:21504
	ds_read_b128 v[214:217], v171 offset:22528
	ds_read_b128 v[218:221], v171 offset:23552
	s_waitcnt vmcnt(8)
	s_waitcnt lgkmcnt(0)
	s_barrier
	v_mfma_f32_16x16x32_bf16 v[92:95], v[148:151], v[190:193], v[92:95]
	v_mfma_f32_16x16x32_bf16 v[92:95], v[152:155], v[194:197], v[92:95]
	v_mfma_f32_16x16x32_bf16 v[88:91], v[160:163], v[194:197], v[88:91]
	v_mfma_f32_16x16x32_bf16 v[88:91], v[156:159], v[190:193], v[88:91]
	v_mfma_f32_16x16x32_bf16 v[28:31], v[174:177], v[190:193], v[28:31]
	v_mfma_f32_16x16x32_bf16 v[28:31], v[178:181], v[194:197], v[28:31]
	v_mfma_f32_16x16x32_bf16 v[24:27], v[186:189], v[194:197], v[24:27]
	v_mfma_f32_16x16x32_bf16 v[24:27], v[182:185], v[190:193], v[24:27]
	v_mfma_f32_16x16x32_bf16 v[16:19], v[182:185], v[198:201], v[16:19]
	v_mfma_f32_16x16x32_bf16 v[16:19], v[186:189], v[202:205], v[16:19]
	v_mfma_f32_16x16x32_bf16 v[20:23], v[178:181], v[202:205], v[20:23]
	v_mfma_f32_16x16x32_bf16 v[20:23], v[174:177], v[198:201], v[20:23]
	v_mfma_f32_16x16x32_bf16 v[80:83], v[156:159], v[198:201], v[80:83]
	v_mfma_f32_16x16x32_bf16 v[80:83], v[160:163], v[202:205], v[80:83]
	v_mfma_f32_16x16x32_bf16 v[84:87], v[152:155], v[202:205], v[84:87]
	v_mfma_f32_16x16x32_bf16 v[84:87], v[148:151], v[198:201], v[84:87]
	v_mfma_f32_16x16x32_bf16 v[76:79], v[148:151], v[206:209], v[76:79]
	v_mfma_f32_16x16x32_bf16 v[76:79], v[152:155], v[210:213], v[76:79]
	v_mfma_f32_16x16x32_bf16 v[72:75], v[160:163], v[210:213], v[72:75]
	v_mfma_f32_16x16x32_bf16 v[72:75], v[156:159], v[206:209], v[72:75]
	v_mfma_f32_16x16x32_bf16 v[12:15], v[174:177], v[206:209], v[12:15]
	v_mfma_f32_16x16x32_bf16 v[12:15], v[178:181], v[210:213], v[12:15]
	v_mfma_f32_16x16x32_bf16 v[8:11], v[186:189], v[210:213], v[8:11]
	v_mfma_f32_16x16x32_bf16 v[8:11], v[182:185], v[206:209], v[8:11]
	v_mfma_f32_16x16x32_bf16 v[0:3], v[182:185], v[214:217], v[0:3]
	v_mfma_f32_16x16x32_bf16 v[0:3], v[186:189], v[218:221], v[0:3]
	v_mfma_f32_16x16x32_bf16 v[4:7], v[178:181], v[218:221], v[4:7]
	v_mfma_f32_16x16x32_bf16 v[4:7], v[174:177], v[214:217], v[4:7]
	v_mfma_f32_16x16x32_bf16 v[64:67], v[156:159], v[214:217], v[64:67]
	s_barrier
	s_setprio 3
	v_mfma_f32_16x16x32_bf16 v[64:67], v[160:163], v[218:221], v[64:67]
	v_mfma_f32_16x16x32_bf16 v[68:71], v[152:155], v[218:221], v[68:71]
	v_mfma_f32_16x16x32_bf16 v[68:71], v[148:151], v[214:217], v[68:71]
	s_setprio 0
	s_add_i32 s35, 0, 0x18000
	v_add_u32_e32 v136, s35, v165
	s_add_i32 s57, 0, 0x1c000
	ds_read_b128 v[148:151], v136
	ds_read_b128 v[152:155], v136 offset:1024
	ds_read_b128 v[156:159], v136 offset:2048
	ds_read_b128 v[160:163], v136 offset:3072
	v_add_u32_e32 v136, s57, v165
	ds_read_b128 v[174:177], v136
	ds_read_b128 v[178:181], v136 offset:1024
	ds_read_b128 v[182:185], v136 offset:2048
	ds_read_b128 v[186:189], v136 offset:3072
	s_add_u32 s28, s28, 0x100000
	s_addc_u32 s29, s29, 0
	s_mov_b32 m0, s43
	v_lshl_add_u64 v[190:191], s[28:29], 0, v[128:129]
	global_load_lds_dwordx4 v[190:191], off
	v_lshl_add_u64 v[190:191], s[28:29], 0, v[132:133]
	s_mov_b32 m0, s44
	s_nop 0
	global_load_lds_dwordx4 v[190:191], off
	ds_read_b128 v[190:193], v171 offset:32768
	ds_read_b128 v[194:197], v171 offset:33792
	ds_read_b128 v[198:201], v171 offset:34816
	ds_read_b128 v[202:205], v171 offset:35840
	ds_read_b128 v[206:209], v171 offset:36864
	ds_read_b128 v[210:213], v171 offset:37888
	ds_read_b128 v[214:217], v171 offset:38912
	ds_read_b128 v[218:221], v171 offset:39936
	s_waitcnt vmcnt(8)
	s_waitcnt lgkmcnt(0)
	s_barrier
	v_mfma_f32_16x16x32_bf16 v[124:127], v[148:151], v[190:193], v[124:127]
	v_mfma_f32_16x16x32_bf16 v[124:127], v[152:155], v[194:197], v[124:127]
	v_mfma_f32_16x16x32_bf16 v[120:123], v[160:163], v[194:197], v[120:123]
	v_mfma_f32_16x16x32_bf16 v[120:123], v[156:159], v[190:193], v[120:123]
	v_mfma_f32_16x16x32_bf16 v[60:63], v[174:177], v[190:193], v[60:63]
	v_mfma_f32_16x16x32_bf16 v[60:63], v[178:181], v[194:197], v[60:63]
	v_mfma_f32_16x16x32_bf16 v[56:59], v[186:189], v[194:197], v[56:59]
	v_mfma_f32_16x16x32_bf16 v[56:59], v[182:185], v[190:193], v[56:59]
	v_mfma_f32_16x16x32_bf16 v[48:51], v[182:185], v[198:201], v[48:51]
	v_mfma_f32_16x16x32_bf16 v[48:51], v[186:189], v[202:205], v[48:51]
	v_mfma_f32_16x16x32_bf16 v[52:55], v[178:181], v[202:205], v[52:55]
	v_mfma_f32_16x16x32_bf16 v[52:55], v[174:177], v[198:201], v[52:55]
	v_mfma_f32_16x16x32_bf16 v[112:115], v[156:159], v[198:201], v[112:115]
	v_mfma_f32_16x16x32_bf16 v[112:115], v[160:163], v[202:205], v[112:115]
	v_mfma_f32_16x16x32_bf16 v[116:119], v[152:155], v[202:205], v[116:119]
	v_mfma_f32_16x16x32_bf16 v[116:119], v[148:151], v[198:201], v[116:119]
	v_mfma_f32_16x16x32_bf16 v[108:111], v[148:151], v[206:209], v[108:111]
	v_mfma_f32_16x16x32_bf16 v[108:111], v[152:155], v[210:213], v[108:111]
	v_mfma_f32_16x16x32_bf16 v[104:107], v[160:163], v[210:213], v[104:107]
	v_mfma_f32_16x16x32_bf16 v[104:107], v[156:159], v[206:209], v[104:107]
	v_mfma_f32_16x16x32_bf16 v[44:47], v[174:177], v[206:209], v[44:47]
	v_mfma_f32_16x16x32_bf16 v[44:47], v[178:181], v[210:213], v[44:47]
	v_mfma_f32_16x16x32_bf16 v[40:43], v[186:189], v[210:213], v[40:43]
	v_mfma_f32_16x16x32_bf16 v[40:43], v[182:185], v[206:209], v[40:43]
	v_mfma_f32_16x16x32_bf16 v[32:35], v[182:185], v[214:217], v[32:35]
	v_mfma_f32_16x16x32_bf16 v[32:35], v[186:189], v[218:221], v[32:35]
	v_mfma_f32_16x16x32_bf16 v[36:39], v[178:181], v[218:221], v[36:39]
	v_mfma_f32_16x16x32_bf16 v[36:39], v[174:177], v[214:217], v[36:39]
	v_mfma_f32_16x16x32_bf16 v[96:99], v[156:159], v[214:217], v[96:99]
	s_barrier
	s_setprio 3
	v_mfma_f32_16x16x32_bf16 v[96:99], v[160:163], v[218:221], v[96:99]
	v_mfma_f32_16x16x32_bf16 v[100:103], v[152:155], v[218:221], v[100:103]
	v_mfma_f32_16x16x32_bf16 v[100:103], v[148:151], v[214:217], v[100:103]
	s_setprio 0
	s_add_i32 s28, s35, s36
	v_lshl_add_u64 v[190:191], v[222:223], 0, s[12:13]
	s_mov_b32 m0, s28
	s_nop 0
	global_load_lds_dwordx4 v[190:191], off
	s_add_i32 m0, s28, 0x2000
	s_add_u32 s26, s26, 0x100800
	v_lshl_add_u64 v[190:191], v[224:225], 0, s[12:13]
	s_addc_u32 s27, s27, 0
	s_add_i32 s28, s57, s36
	global_load_lds_dwordx4 v[190:191], off
	v_lshl_add_u64 v[190:191], s[26:27], 0, v[130:131]
	s_mov_b32 m0, s28
	s_nop 0
	global_load_lds_dwordx4 v[190:191], off
	v_lshl_add_u64 v[190:191], s[26:27], 0, v[134:135]
	s_add_i32 m0, s28, 0x2000
	s_nop 0
	global_load_lds_dwordx4 v[190:191], off
	v_lshl_add_u64 v[190:191], v[226:227], 0, s[12:13]
	s_mov_b32 m0, s49
	s_nop 0
	global_load_lds_dwordx4 v[190:191], off
	v_lshl_add_u64 v[190:191], v[228:229], 0, s[12:13]
	s_mov_b32 m0, s50
	s_nop 0
	global_load_lds_dwordx4 v[190:191], off
	ds_read_b128 v[190:193], v171 offset:49152
	ds_read_b128 v[194:197], v171 offset:50176
	ds_read_b128 v[198:201], v171 offset:51200
	ds_read_b128 v[202:205], v171 offset:52224
	ds_read_b128 v[206:209], v171 offset:53248
	ds_read_b128 v[210:213], v171 offset:54272
	ds_read_b128 v[214:217], v171 offset:55296
	ds_read_b128 v[218:221], v171 offset:56320
	s_waitcnt vmcnt(8)
	s_waitcnt lgkmcnt(0)
	s_barrier
	v_mfma_f32_16x16x32_bf16 v[92:95], v[148:151], v[190:193], v[92:95]
	v_mfma_f32_16x16x32_bf16 v[92:95], v[152:155], v[194:197], v[92:95]
	v_mfma_f32_16x16x32_bf16 v[88:91], v[160:163], v[194:197], v[88:91]
	v_mfma_f32_16x16x32_bf16 v[88:91], v[156:159], v[190:193], v[88:91]
	v_mfma_f32_16x16x32_bf16 v[28:31], v[174:177], v[190:193], v[28:31]
	v_mfma_f32_16x16x32_bf16 v[28:31], v[178:181], v[194:197], v[28:31]
	v_mfma_f32_16x16x32_bf16 v[24:27], v[186:189], v[194:197], v[24:27]
	v_mfma_f32_16x16x32_bf16 v[24:27], v[182:185], v[190:193], v[24:27]
	v_mfma_f32_16x16x32_bf16 v[16:19], v[182:185], v[198:201], v[16:19]
	v_mfma_f32_16x16x32_bf16 v[16:19], v[186:189], v[202:205], v[16:19]
	v_mfma_f32_16x16x32_bf16 v[20:23], v[178:181], v[202:205], v[20:23]
	v_mfma_f32_16x16x32_bf16 v[20:23], v[174:177], v[198:201], v[20:23]
	v_mfma_f32_16x16x32_bf16 v[80:83], v[156:159], v[198:201], v[80:83]
	v_mfma_f32_16x16x32_bf16 v[80:83], v[160:163], v[202:205], v[80:83]
	v_mfma_f32_16x16x32_bf16 v[84:87], v[152:155], v[202:205], v[84:87]
	v_mfma_f32_16x16x32_bf16 v[84:87], v[148:151], v[198:201], v[84:87]
	v_mfma_f32_16x16x32_bf16 v[76:79], v[148:151], v[206:209], v[76:79]
	v_mfma_f32_16x16x32_bf16 v[76:79], v[152:155], v[210:213], v[76:79]
	v_mfma_f32_16x16x32_bf16 v[72:75], v[160:163], v[210:213], v[72:75]
	v_mfma_f32_16x16x32_bf16 v[72:75], v[156:159], v[206:209], v[72:75]
	v_mfma_f32_16x16x32_bf16 v[12:15], v[174:177], v[206:209], v[12:15]
	v_mfma_f32_16x16x32_bf16 v[12:15], v[178:181], v[210:213], v[12:15]
	v_mfma_f32_16x16x32_bf16 v[8:11], v[186:189], v[210:213], v[8:11]
	v_mfma_f32_16x16x32_bf16 v[8:11], v[182:185], v[206:209], v[8:11]
	v_mfma_f32_16x16x32_bf16 v[0:3], v[182:185], v[214:217], v[0:3]
	v_mfma_f32_16x16x32_bf16 v[0:3], v[186:189], v[218:221], v[0:3]
	v_mfma_f32_16x16x32_bf16 v[4:7], v[178:181], v[218:221], v[4:7]
	v_mfma_f32_16x16x32_bf16 v[4:7], v[174:177], v[214:217], v[4:7]
	v_mfma_f32_16x16x32_bf16 v[64:67], v[156:159], v[214:217], v[64:67]
	s_barrier
	s_setprio 3
	v_mfma_f32_16x16x32_bf16 v[64:67], v[160:163], v[218:221], v[64:67]
	v_mfma_f32_16x16x32_bf16 v[68:71], v[152:155], v[218:221], v[68:71]
	v_mfma_f32_16x16x32_bf16 v[68:71], v[148:151], v[214:217], v[68:71]
	s_setprio 0
	s_add_i32 s34, s34, 2
	s_add_u32 s6, s6, 0x1000
	s_addc_u32 s7, s7, 0
	s_add_u32 s30, s30, 0x1000
	s_addc_u32 s31, s31, 0
	s_cmp_gt_u32 s34, 61
	s_cbranch_scc0 .LBB0_200

.LBB0_333:
	ds_read_b128 v[144:147], v152
	ds_read_b128 v[156:159], v152 offset:1024
	ds_read_b128 v[160:163], v152 offset:2048
	ds_read_b128 v[164:167], v152 offset:3072
	ds_read_b128 v[168:171], v153
	ds_read_b128 v[172:175], v153 offset:1024
	ds_read_b128 v[176:179], v153 offset:2048
	ds_read_b128 v[180:183], v153 offset:3072
	s_add_u32 s28, s24, 0x100
	s_addc_u32 s29, s25, 0
	s_cmp_eq_u32 s56, 60
	s_cselect_b32 s35, s13, s29
	s_cselect_b32 s34, s52, s28
	s_cselect_b32 s31, s11, s55
	s_cselect_b32 s30, s53, s54
	v_lshl_add_u64 v[184:185], s[24:25], 0, v[136:137]
	s_add_i32 m0, s21, 0xc000
	s_nop 0
	global_load_lds_dwordx4 v[184:185], off
	v_lshl_add_u64 v[184:185], s[24:25], 0, v[138:139]
	s_add_i32 m0, s21, 0xe000
	s_nop 0
	global_load_lds_dwordx4 v[184:185], off
	ds_read_b128 v[184:187], v154
	ds_read_b128 v[188:191], v154 offset:1024
	ds_read_b128 v[192:195], v154 offset:2048
	ds_read_b128 v[196:199], v154 offset:3072
	ds_read_b128 v[200:203], v154 offset:4096
	ds_read_b128 v[204:207], v154 offset:5120
	ds_read_b128 v[208:211], v154 offset:6144
	ds_read_b128 v[212:215], v154 offset:7168
	s_waitcnt vmcnt(8)
	s_waitcnt lgkmcnt(0)
	s_barrier
	v_mfma_f32_16x16x32_bf16 v[124:127], v[144:147], v[184:187], v[124:127]
	v_mfma_f32_16x16x32_bf16 v[124:127], v[156:159], v[188:191], v[124:127]
	v_mfma_f32_16x16x32_bf16 v[120:123], v[164:167], v[188:191], v[120:123]
	v_mfma_f32_16x16x32_bf16 v[120:123], v[160:163], v[184:187], v[120:123]
	v_mfma_f32_16x16x32_bf16 v[112:115], v[168:171], v[184:187], v[112:115]
	v_mfma_f32_16x16x32_bf16 v[112:115], v[172:175], v[188:191], v[112:115]
	v_mfma_f32_16x16x32_bf16 v[104:107], v[180:183], v[188:191], v[104:107]
	v_mfma_f32_16x16x32_bf16 v[104:107], v[176:179], v[184:187], v[104:107]
	v_mfma_f32_16x16x32_bf16 v[88:91], v[176:179], v[192:195], v[88:91]
	v_mfma_f32_16x16x32_bf16 v[88:91], v[180:183], v[196:199], v[88:91]
	v_mfma_f32_16x16x32_bf16 v[96:99], v[172:175], v[196:199], v[96:99]
	v_mfma_f32_16x16x32_bf16 v[96:99], v[168:171], v[192:195], v[96:99]
	v_mfma_f32_16x16x32_bf16 v[108:111], v[160:163], v[192:195], v[108:111]
	v_mfma_f32_16x16x32_bf16 v[108:111], v[164:167], v[196:199], v[108:111]
	v_mfma_f32_16x16x32_bf16 v[116:119], v[156:159], v[196:199], v[116:119]
	v_mfma_f32_16x16x32_bf16 v[116:119], v[144:147], v[192:195], v[116:119]
	v_mfma_f32_16x16x32_bf16 v[100:103], v[144:147], v[200:203], v[100:103]
	v_mfma_f32_16x16x32_bf16 v[100:103], v[156:159], v[204:207], v[100:103]
	v_mfma_f32_16x16x32_bf16 v[92:95], v[164:167], v[204:207], v[92:95]
	v_mfma_f32_16x16x32_bf16 v[92:95], v[160:163], v[200:203], v[92:95]
	v_mfma_f32_16x16x32_bf16 v[80:83], v[168:171], v[200:203], v[80:83]
	v_mfma_f32_16x16x32_bf16 v[80:83], v[172:175], v[204:207], v[80:83]
	v_mfma_f32_16x16x32_bf16 v[72:75], v[180:183], v[204:207], v[72:75]
	v_mfma_f32_16x16x32_bf16 v[72:75], v[176:179], v[200:203], v[72:75]
	v_mfma_f32_16x16x32_bf16 v[64:67], v[176:179], v[208:211], v[64:67]
	v_mfma_f32_16x16x32_bf16 v[64:67], v[180:183], v[212:215], v[64:67]
	v_mfma_f32_16x16x32_bf16 v[68:71], v[172:175], v[212:215], v[68:71]
	v_mfma_f32_16x16x32_bf16 v[68:71], v[168:171], v[208:211], v[68:71]
	v_mfma_f32_16x16x32_bf16 v[76:79], v[160:163], v[208:211], v[76:79]
	s_barrier
	s_setprio 3
	v_mfma_f32_16x16x32_bf16 v[76:79], v[164:167], v[212:215], v[76:79]
	v_mfma_f32_16x16x32_bf16 v[84:87], v[156:159], v[212:215], v[84:87]
	v_mfma_f32_16x16x32_bf16 v[84:87], v[144:147], v[208:211], v[84:87]
	s_setprio 0
	s_add_i32 s24, s49, s41
	v_lshl_add_u64 v[216:217], s[30:31], 0, v[130:131]
	s_mov_b32 m0, s24
	v_lshl_add_u64 v[218:219], s[30:31], 0, v[134:135]
	global_load_lds_dwordx4 v[216:217], off
	s_add_i32 m0, s24, 0x2000
	s_add_u32 s24, s30, 0x100000
	s_addc_u32 s25, s31, 0
	s_add_i32 s57, s50, s41
	global_load_lds_dwordx4 v[218:219], off
	v_lshl_add_u64 v[184:185], s[24:25], 0, v[130:131]
	s_mov_b32 m0, s57
	v_lshl_add_u64 v[220:221], s[34:35], 0, v[128:129]
	global_load_lds_dwordx4 v[184:185], off
	v_lshl_add_u64 v[184:185], s[24:25], 0, v[134:135]
	s_add_i32 m0, s57, 0x2000
	v_lshl_add_u64 v[222:223], s[34:35], 0, v[132:133]
	global_load_lds_dwordx4 v[184:185], off
	s_mov_b32 m0, s21
	s_nop 0
	global_load_lds_dwordx4 v[220:221], off
	s_mov_b32 m0, s42
	s_nop 0
	global_load_lds_dwordx4 v[222:223], off
	ds_read_b128 v[184:187], v154 offset:16384
	ds_read_b128 v[188:191], v154 offset:17408
	ds_read_b128 v[192:195], v154 offset:18432
	ds_read_b128 v[196:199], v154 offset:19456
	ds_read_b128 v[200:203], v154 offset:20480
	ds_read_b128 v[204:207], v154 offset:21504
	ds_read_b128 v[208:211], v154 offset:22528
	ds_read_b128 v[212:215], v154 offset:23552
	s_waitcnt vmcnt(8)
	s_waitcnt lgkmcnt(0)
	s_barrier
	v_mfma_f32_16x16x32_bf16 v[60:63], v[144:147], v[184:187], v[60:63]
	v_mfma_f32_16x16x32_bf16 v[60:63], v[156:159], v[188:191], v[60:63]
	v_mfma_f32_16x16x32_bf16 v[56:59], v[164:167], v[188:191], v[56:59]
	v_mfma_f32_16x16x32_bf16 v[56:59], v[160:163], v[184:187], v[56:59]
	v_mfma_f32_16x16x32_bf16 v[48:51], v[168:171], v[184:187], v[48:51]
	v_mfma_f32_16x16x32_bf16 v[48:51], v[172:175], v[188:191], v[48:51]
	v_mfma_f32_16x16x32_bf16 v[40:43], v[180:183], v[188:191], v[40:43]
	v_mfma_f32_16x16x32_bf16 v[40:43], v[176:179], v[184:187], v[40:43]
	v_mfma_f32_16x16x32_bf16 v[24:27], v[176:179], v[192:195], v[24:27]
	v_mfma_f32_16x16x32_bf16 v[24:27], v[180:183], v[196:199], v[24:27]
	v_mfma_f32_16x16x32_bf16 v[32:35], v[172:175], v[196:199], v[32:35]
	v_mfma_f32_16x16x32_bf16 v[32:35], v[168:171], v[192:195], v[32:35]
	v_mfma_f32_16x16x32_bf16 v[44:47], v[160:163], v[192:195], v[44:47]
	v_mfma_f32_16x16x32_bf16 v[44:47], v[164:167], v[196:199], v[44:47]
	v_mfma_f32_16x16x32_bf16 v[52:55], v[156:159], v[196:199], v[52:55]
	v_mfma_f32_16x16x32_bf16 v[52:55], v[144:147], v[192:195], v[52:55]
	v_mfma_f32_16x16x32_bf16 v[36:39], v[144:147], v[200:203], v[36:39]
	v_mfma_f32_16x16x32_bf16 v[36:39], v[156:159], v[204:207], v[36:39]
	v_mfma_f32_16x16x32_bf16 v[28:31], v[164:167], v[204:207], v[28:31]
	v_mfma_f32_16x16x32_bf16 v[28:31], v[160:163], v[200:203], v[28:31]
	v_mfma_f32_16x16x32_bf16 v[16:19], v[168:171], v[200:203], v[16:19]
	v_mfma_f32_16x16x32_bf16 v[16:19], v[172:175], v[204:207], v[16:19]
	v_mfma_f32_16x16x32_bf16 v[8:11], v[180:183], v[204:207], v[8:11]
	v_mfma_f32_16x16x32_bf16 v[8:11], v[176:179], v[200:203], v[8:11]
	v_mfma_f32_16x16x32_bf16 v[0:3], v[176:179], v[208:211], v[0:3]
	v_mfma_f32_16x16x32_bf16 v[0:3], v[180:183], v[212:215], v[0:3]
	v_mfma_f32_16x16x32_bf16 v[4:7], v[172:175], v[212:215], v[4:7]
	v_mfma_f32_16x16x32_bf16 v[4:7], v[168:171], v[208:211], v[4:7]
	v_mfma_f32_16x16x32_bf16 v[12:15], v[160:163], v[208:211], v[12:15]
	s_barrier
	s_setprio 3
	v_mfma_f32_16x16x32_bf16 v[12:15], v[164:167], v[212:215], v[12:15]
	v_mfma_f32_16x16x32_bf16 v[20:23], v[156:159], v[212:215], v[20:23]
	v_mfma_f32_16x16x32_bf16 v[20:23], v[144:147], v[208:211], v[20:23]
	s_setprio 0
	s_add_i32 s57, 0, 0x18000
	v_add_u32_e32 v155, s57, v149
	s_add_i32 s58, 0, 0x1c000
	ds_read_b128 v[144:147], v155
	ds_read_b128 v[156:159], v155 offset:1024
	ds_read_b128 v[160:163], v155 offset:2048
	ds_read_b128 v[164:167], v155 offset:3072
	v_add_u32_e32 v155, s58, v149
	ds_read_b128 v[168:171], v155
	ds_read_b128 v[172:175], v155 offset:1024
	ds_read_b128 v[176:179], v155 offset:2048
	ds_read_b128 v[180:183], v155 offset:3072
	s_add_u32 s24, s34, 0x100000
	s_addc_u32 s25, s35, 0
	s_mov_b32 m0, s43
	v_lshl_add_u64 v[184:185], s[24:25], 0, v[128:129]
	global_load_lds_dwordx4 v[184:185], off
	v_lshl_add_u64 v[184:185], s[24:25], 0, v[132:133]
	s_mov_b32 m0, s44
	s_nop 0
	global_load_lds_dwordx4 v[184:185], off
	ds_read_b128 v[184:187], v154 offset:32768
	ds_read_b128 v[188:191], v154 offset:33792
	ds_read_b128 v[192:195], v154 offset:34816
	ds_read_b128 v[196:199], v154 offset:35840
	ds_read_b128 v[200:203], v154 offset:36864
	ds_read_b128 v[204:207], v154 offset:37888
	ds_read_b128 v[208:211], v154 offset:38912
	ds_read_b128 v[212:215], v154 offset:39936
	s_waitcnt vmcnt(8)
	s_waitcnt lgkmcnt(0)
	s_barrier
	v_mfma_f32_16x16x32_bf16 v[124:127], v[144:147], v[184:187], v[124:127]
	v_mfma_f32_16x16x32_bf16 v[124:127], v[156:159], v[188:191], v[124:127]
	v_mfma_f32_16x16x32_bf16 v[120:123], v[164:167], v[188:191], v[120:123]
	v_mfma_f32_16x16x32_bf16 v[120:123], v[160:163], v[184:187], v[120:123]
	v_mfma_f32_16x16x32_bf16 v[112:115], v[168:171], v[184:187], v[112:115]
	v_mfma_f32_16x16x32_bf16 v[112:115], v[172:175], v[188:191], v[112:115]
	v_mfma_f32_16x16x32_bf16 v[104:107], v[180:183], v[188:191], v[104:107]
	v_mfma_f32_16x16x32_bf16 v[104:107], v[176:179], v[184:187], v[104:107]
	v_mfma_f32_16x16x32_bf16 v[88:91], v[176:179], v[192:195], v[88:91]
	v_mfma_f32_16x16x32_bf16 v[88:91], v[180:183], v[196:199], v[88:91]
	v_mfma_f32_16x16x32_bf16 v[96:99], v[172:175], v[196:199], v[96:99]
	v_mfma_f32_16x16x32_bf16 v[96:99], v[168:171], v[192:195], v[96:99]
	v_mfma_f32_16x16x32_bf16 v[108:111], v[160:163], v[192:195], v[108:111]
	v_mfma_f32_16x16x32_bf16 v[108:111], v[164:167], v[196:199], v[108:111]
	v_mfma_f32_16x16x32_bf16 v[116:119], v[156:159], v[196:199], v[116:119]
	v_mfma_f32_16x16x32_bf16 v[116:119], v[144:147], v[192:195], v[116:119]
	v_mfma_f32_16x16x32_bf16 v[100:103], v[144:147], v[200:203], v[100:103]
	v_mfma_f32_16x16x32_bf16 v[100:103], v[156:159], v[204:207], v[100:103]
	v_mfma_f32_16x16x32_bf16 v[92:95], v[164:167], v[204:207], v[92:95]
	v_mfma_f32_16x16x32_bf16 v[92:95], v[160:163], v[200:203], v[92:95]
	v_mfma_f32_16x16x32_bf16 v[80:83], v[168:171], v[200:203], v[80:83]
	v_mfma_f32_16x16x32_bf16 v[80:83], v[172:175], v[204:207], v[80:83]
	v_mfma_f32_16x16x32_bf16 v[72:75], v[180:183], v[204:207], v[72:75]
	v_mfma_f32_16x16x32_bf16 v[72:75], v[176:179], v[200:203], v[72:75]
	v_mfma_f32_16x16x32_bf16 v[64:67], v[176:179], v[208:211], v[64:67]
	v_mfma_f32_16x16x32_bf16 v[64:67], v[180:183], v[212:215], v[64:67]
	v_mfma_f32_16x16x32_bf16 v[68:71], v[172:175], v[212:215], v[68:71]
	v_mfma_f32_16x16x32_bf16 v[68:71], v[168:171], v[208:211], v[68:71]
	v_mfma_f32_16x16x32_bf16 v[76:79], v[160:163], v[208:211], v[76:79]
	s_barrier
	s_setprio 3
	v_mfma_f32_16x16x32_bf16 v[76:79], v[164:167], v[212:215], v[76:79]
	v_mfma_f32_16x16x32_bf16 v[84:87], v[156:159], v[212:215], v[84:87]
	v_mfma_f32_16x16x32_bf16 v[84:87], v[144:147], v[208:211], v[84:87]
	s_setprio 0
	s_add_i32 s24, s57, s41
	v_lshl_add_u64 v[184:185], v[216:217], 0, s[8:9]
	s_mov_b32 m0, s24
	s_nop 0
	global_load_lds_dwordx4 v[184:185], off
	s_add_i32 m0, s24, 0x2000
	s_add_u32 s24, s30, 0x100080
	v_lshl_add_u64 v[184:185], v[218:219], 0, s[8:9]
	s_addc_u32 s25, s31, 0
	s_add_i32 s30, s58, s41
	global_load_lds_dwordx4 v[184:185], off
	v_lshl_add_u64 v[184:185], s[24:25], 0, v[130:131]
	s_mov_b32 m0, s30
	s_nop 0
	global_load_lds_dwordx4 v[184:185], off
	v_lshl_add_u64 v[184:185], s[24:25], 0, v[134:135]
	s_add_i32 m0, s30, 0x2000
	s_nop 0
	global_load_lds_dwordx4 v[184:185], off
	v_lshl_add_u64 v[184:185], v[220:221], 0, s[8:9]
	s_mov_b32 m0, s46
	s_nop 0
	global_load_lds_dwordx4 v[184:185], off
	v_lshl_add_u64 v[184:185], v[222:223], 0, s[8:9]
	s_mov_b32 m0, s47
	s_nop 0
	global_load_lds_dwordx4 v[184:185], off
	ds_read_b128 v[184:187], v154 offset:49152
	ds_read_b128 v[188:191], v154 offset:50176
	ds_read_b128 v[192:195], v154 offset:51200
	ds_read_b128 v[196:199], v154 offset:52224
	ds_read_b128 v[200:203], v154 offset:53248
	ds_read_b128 v[204:207], v154 offset:54272
	ds_read_b128 v[208:211], v154 offset:55296
	ds_read_b128 v[212:215], v154 offset:56320
	s_waitcnt vmcnt(8)
	s_waitcnt lgkmcnt(0)
	s_barrier
	v_mfma_f32_16x16x32_bf16 v[60:63], v[144:147], v[184:187], v[60:63]
	v_mfma_f32_16x16x32_bf16 v[60:63], v[156:159], v[188:191], v[60:63]
	v_mfma_f32_16x16x32_bf16 v[56:59], v[164:167], v[188:191], v[56:59]
	v_mfma_f32_16x16x32_bf16 v[56:59], v[160:163], v[184:187], v[56:59]
	v_mfma_f32_16x16x32_bf16 v[48:51], v[168:171], v[184:187], v[48:51]
	v_mfma_f32_16x16x32_bf16 v[48:51], v[172:175], v[188:191], v[48:51]
	v_mfma_f32_16x16x32_bf16 v[40:43], v[180:183], v[188:191], v[40:43]
	v_mfma_f32_16x16x32_bf16 v[40:43], v[176:179], v[184:187], v[40:43]
	v_mfma_f32_16x16x32_bf16 v[24:27], v[176:179], v[192:195], v[24:27]
	v_mfma_f32_16x16x32_bf16 v[24:27], v[180:183], v[196:199], v[24:27]
	v_mfma_f32_16x16x32_bf16 v[32:35], v[172:175], v[196:199], v[32:35]
	v_mfma_f32_16x16x32_bf16 v[32:35], v[168:171], v[192:195], v[32:35]
	v_mfma_f32_16x16x32_bf16 v[44:47], v[160:163], v[192:195], v[44:47]
	v_mfma_f32_16x16x32_bf16 v[44:47], v[164:167], v[196:199], v[44:47]
	v_mfma_f32_16x16x32_bf16 v[52:55], v[156:159], v[196:199], v[52:55]
	v_mfma_f32_16x16x32_bf16 v[52:55], v[144:147], v[192:195], v[52:55]
	v_mfma_f32_16x16x32_bf16 v[36:39], v[144:147], v[200:203], v[36:39]
	v_mfma_f32_16x16x32_bf16 v[36:39], v[156:159], v[204:207], v[36:39]
	v_mfma_f32_16x16x32_bf16 v[28:31], v[164:167], v[204:207], v[28:31]
	v_mfma_f32_16x16x32_bf16 v[28:31], v[160:163], v[200:203], v[28:31]
	v_mfma_f32_16x16x32_bf16 v[16:19], v[168:171], v[200:203], v[16:19]
	v_mfma_f32_16x16x32_bf16 v[16:19], v[172:175], v[204:207], v[16:19]
	v_mfma_f32_16x16x32_bf16 v[8:11], v[180:183], v[204:207], v[8:11]
	v_mfma_f32_16x16x32_bf16 v[8:11], v[176:179], v[200:203], v[8:11]
	v_mfma_f32_16x16x32_bf16 v[0:3], v[176:179], v[208:211], v[0:3]
	v_mfma_f32_16x16x32_bf16 v[0:3], v[180:183], v[212:215], v[0:3]
	v_mfma_f32_16x16x32_bf16 v[4:7], v[172:175], v[212:215], v[4:7]
	v_mfma_f32_16x16x32_bf16 v[4:7], v[168:171], v[208:211], v[4:7]
	v_mfma_f32_16x16x32_bf16 v[12:15], v[160:163], v[208:211], v[12:15]
	s_barrier
	s_setprio 3
	v_mfma_f32_16x16x32_bf16 v[12:15], v[164:167], v[212:215], v[12:15]
	v_mfma_f32_16x16x32_bf16 v[20:23], v[156:159], v[212:215], v[20:23]
	v_mfma_f32_16x16x32_bf16 v[20:23], v[144:147], v[208:211], v[20:23]
	s_setprio 0
	s_add_i32 s56, s56, 2
	s_add_u32 s54, s54, 0x100
	s_addc_u32 s55, s55, 0
	s_cmp_gt_u32 s56, 61
	s_mov_b64 s[24:25], s[28:29]
	s_cbranch_scc0 .LBB0_333
	s_and_b64 vcc, exec, s[0:1]
	s_cbranch_vccz .LBB0_336
	s_barrier

.LBB0_1202:
	ds_read_b128 v[128:131], v176
	ds_read_b128 v[132:135], v176 offset:1024
	ds_read_b128 v[136:139], v176 offset:2048
	ds_read_b128 v[140:143], v176 offset:3072
	ds_read_b128 v[144:147], v177
	ds_read_b128 v[148:151], v177 offset:1024
	ds_read_b128 v[180:183], v177 offset:2048
	ds_read_b128 v[184:187], v177 offset:3072
	s_add_u32 s30, s28, 0xfff00080
	s_addc_u32 s31, s29, -1
	s_cmp_eq_u32 s40, 60
	s_cselect_b32 s35, s23, s31
	s_cselect_b32 s34, s36, s30
	s_cselect_b32 s31, s21, s39
	s_cselect_b32 s30, s37, s38
	v_lshl_add_u64 v[172:173], s[28:29], 0, v[164:165]
	s_add_i32 m0, s7, 0xc000
	s_nop 0
	global_load_lds_dwordx4 v[172:173], off
	v_lshl_add_u64 v[172:173], s[28:29], 0, v[166:167]
	s_add_i32 m0, s7, 0xe000
	s_nop 0
	global_load_lds_dwordx4 v[172:173], off
	ds_read_b128 v[188:191], v178
	ds_read_b128 v[192:195], v178 offset:1024
	ds_read_b128 v[196:199], v178 offset:2048
	ds_read_b128 v[200:203], v178 offset:3072
	ds_read_b128 v[204:207], v178 offset:4096
	ds_read_b128 v[208:211], v178 offset:5120
	ds_read_b128 v[212:215], v178 offset:6144
	ds_read_b128 v[216:219], v178 offset:7168
	s_waitcnt vmcnt(8)
	s_waitcnt lgkmcnt(0)
	s_barrier
	v_mfma_f32_16x16x32_bf16 v[124:127], v[128:131], v[188:191], v[124:127]
	v_mfma_f32_16x16x32_bf16 v[124:127], v[132:135], v[192:195], v[124:127]
	v_mfma_f32_16x16x32_bf16 v[120:123], v[140:143], v[192:195], v[120:123]
	v_mfma_f32_16x16x32_bf16 v[120:123], v[136:139], v[188:191], v[120:123]
	v_mfma_f32_16x16x32_bf16 v[116:119], v[144:147], v[188:191], v[116:119]
	v_mfma_f32_16x16x32_bf16 v[116:119], v[148:151], v[192:195], v[116:119]
	v_mfma_f32_16x16x32_bf16 v[112:115], v[184:187], v[192:195], v[112:115]
	v_mfma_f32_16x16x32_bf16 v[112:115], v[180:183], v[188:191], v[112:115]
	v_mfma_f32_16x16x32_bf16 v[96:99], v[180:183], v[196:199], v[96:99]
	v_mfma_f32_16x16x32_bf16 v[96:99], v[184:187], v[200:203], v[96:99]
	v_mfma_f32_16x16x32_bf16 v[100:103], v[148:151], v[200:203], v[100:103]
	v_mfma_f32_16x16x32_bf16 v[100:103], v[144:147], v[196:199], v[100:103]
	v_mfma_f32_16x16x32_bf16 v[104:107], v[136:139], v[196:199], v[104:107]
	v_mfma_f32_16x16x32_bf16 v[104:107], v[140:143], v[200:203], v[104:107]
	v_mfma_f32_16x16x32_bf16 v[108:111], v[132:135], v[200:203], v[108:111]
	v_mfma_f32_16x16x32_bf16 v[108:111], v[128:131], v[196:199], v[108:111]
	v_mfma_f32_16x16x32_bf16 v[92:95], v[128:131], v[204:207], v[92:95]
	v_mfma_f32_16x16x32_bf16 v[92:95], v[132:135], v[208:211], v[92:95]
	v_mfma_f32_16x16x32_bf16 v[88:91], v[140:143], v[208:211], v[88:91]
	v_mfma_f32_16x16x32_bf16 v[88:91], v[136:139], v[204:207], v[88:91]
	v_mfma_f32_16x16x32_bf16 v[84:87], v[144:147], v[204:207], v[84:87]
	v_mfma_f32_16x16x32_bf16 v[84:87], v[148:151], v[208:211], v[84:87]
	v_mfma_f32_16x16x32_bf16 v[80:83], v[184:187], v[208:211], v[80:83]
	v_mfma_f32_16x16x32_bf16 v[80:83], v[180:183], v[204:207], v[80:83]
	v_mfma_f32_16x16x32_bf16 v[64:67], v[180:183], v[212:215], v[64:67]
	v_mfma_f32_16x16x32_bf16 v[64:67], v[184:187], v[216:219], v[64:67]
	v_mfma_f32_16x16x32_bf16 v[68:71], v[148:151], v[216:219], v[68:71]
	v_mfma_f32_16x16x32_bf16 v[68:71], v[144:147], v[212:215], v[68:71]
	v_mfma_f32_16x16x32_bf16 v[72:75], v[136:139], v[212:215], v[72:75]
	s_barrier
	s_setprio 3
	v_mfma_f32_16x16x32_bf16 v[72:75], v[140:143], v[216:219], v[72:75]
	v_mfma_f32_16x16x32_bf16 v[76:79], v[132:135], v[216:219], v[76:79]
	v_mfma_f32_16x16x32_bf16 v[76:79], v[128:131], v[212:215], v[76:79]
	s_setprio 0
	s_add_i32 s41, s68, s33
	v_lshl_add_u64 v[172:173], s[30:31], 0, v[154:155]
	s_mov_b32 m0, s41
	v_lshl_add_u64 v[220:221], s[30:31], 0, v[158:159]
	global_load_lds_dwordx4 v[172:173], off
	s_add_i32 m0, s41, 0x2000
	s_add_u32 s42, s30, 0x100000
	s_addc_u32 s43, s31, 0
	s_add_i32 s41, s69, s33
	global_load_lds_dwordx4 v[220:221], off
	v_lshl_add_u64 v[188:189], s[42:43], 0, v[154:155]
	s_mov_b32 m0, s41
	v_lshl_add_u64 v[222:223], s[34:35], 0, v[152:153]
	global_load_lds_dwordx4 v[188:189], off
	v_lshl_add_u64 v[188:189], s[42:43], 0, v[158:159]
	s_add_i32 m0, s41, 0x2000
	v_lshl_add_u64 v[224:225], s[34:35], 0, v[156:157]
	global_load_lds_dwordx4 v[188:189], off
	s_mov_b32 m0, s7
	s_nop 0
	global_load_lds_dwordx4 v[222:223], off
	s_mov_b32 m0, s59
	s_nop 0
	global_load_lds_dwordx4 v[224:225], off
	ds_read_b128 v[188:191], v178 offset:16384
	ds_read_b128 v[192:195], v178 offset:17408
	ds_read_b128 v[196:199], v178 offset:18432
	ds_read_b128 v[200:203], v178 offset:19456
	ds_read_b128 v[204:207], v178 offset:20480
	ds_read_b128 v[208:211], v178 offset:21504
	ds_read_b128 v[212:215], v178 offset:22528
	ds_read_b128 v[216:219], v178 offset:23552
	s_waitcnt vmcnt(8)
	s_waitcnt lgkmcnt(0)
	s_barrier
	v_mfma_f32_16x16x32_bf16 v[60:63], v[128:131], v[188:191], v[60:63]
	v_mfma_f32_16x16x32_bf16 v[60:63], v[132:135], v[192:195], v[60:63]
	v_mfma_f32_16x16x32_bf16 v[56:59], v[140:143], v[192:195], v[56:59]
	v_mfma_f32_16x16x32_bf16 v[56:59], v[136:139], v[188:191], v[56:59]
	v_mfma_f32_16x16x32_bf16 v[52:55], v[144:147], v[188:191], v[52:55]
	v_mfma_f32_16x16x32_bf16 v[52:55], v[148:151], v[192:195], v[52:55]
	v_mfma_f32_16x16x32_bf16 v[48:51], v[184:187], v[192:195], v[48:51]
	v_mfma_f32_16x16x32_bf16 v[48:51], v[180:183], v[188:191], v[48:51]
	v_mfma_f32_16x16x32_bf16 v[32:35], v[180:183], v[196:199], v[32:35]
	v_mfma_f32_16x16x32_bf16 v[32:35], v[184:187], v[200:203], v[32:35]
	v_mfma_f32_16x16x32_bf16 v[36:39], v[148:151], v[200:203], v[36:39]
	v_mfma_f32_16x16x32_bf16 v[36:39], v[144:147], v[196:199], v[36:39]
	v_mfma_f32_16x16x32_bf16 v[40:43], v[136:139], v[196:199], v[40:43]
	v_mfma_f32_16x16x32_bf16 v[40:43], v[140:143], v[200:203], v[40:43]
	v_mfma_f32_16x16x32_bf16 v[44:47], v[132:135], v[200:203], v[44:47]
	v_mfma_f32_16x16x32_bf16 v[44:47], v[128:131], v[196:199], v[44:47]
	v_mfma_f32_16x16x32_bf16 v[28:31], v[128:131], v[204:207], v[28:31]
	v_mfma_f32_16x16x32_bf16 v[28:31], v[132:135], v[208:211], v[28:31]
	v_mfma_f32_16x16x32_bf16 v[24:27], v[140:143], v[208:211], v[24:27]
	v_mfma_f32_16x16x32_bf16 v[24:27], v[136:139], v[204:207], v[24:27]
	v_mfma_f32_16x16x32_bf16 v[20:23], v[144:147], v[204:207], v[20:23]
	v_mfma_f32_16x16x32_bf16 v[20:23], v[148:151], v[208:211], v[20:23]
	v_mfma_f32_16x16x32_bf16 v[16:19], v[184:187], v[208:211], v[16:19]
	v_mfma_f32_16x16x32_bf16 v[16:19], v[180:183], v[204:207], v[16:19]
	v_mfma_f32_16x16x32_bf16 v[0:3], v[180:183], v[212:215], v[0:3]
	v_mfma_f32_16x16x32_bf16 v[0:3], v[184:187], v[216:219], v[0:3]
	v_mfma_f32_16x16x32_bf16 v[4:7], v[148:151], v[216:219], v[4:7]
	v_mfma_f32_16x16x32_bf16 v[4:7], v[144:147], v[212:215], v[4:7]
	v_mfma_f32_16x16x32_bf16 v[8:11], v[136:139], v[212:215], v[8:11]
	s_barrier
	s_setprio 3
	v_mfma_f32_16x16x32_bf16 v[8:11], v[140:143], v[216:219], v[8:11]
	v_mfma_f32_16x16x32_bf16 v[12:15], v[132:135], v[216:219], v[12:15]
	v_mfma_f32_16x16x32_bf16 v[12:15], v[128:131], v[212:215], v[12:15]
	s_setprio 0
	s_add_i32 s41, 0, 0x18000
	s_add_i32 s42, 0, 0x1c000
	v_add_u32_e32 v140, s41, v174
	v_add_u32_e32 v184, s42, v174
	ds_read_b128 v[128:131], v140
	ds_read_b128 v[132:135], v140 offset:1024
	ds_read_b128 v[136:139], v140 offset:2048
	ds_read_b128 v[140:143], v140 offset:3072
	ds_read_b128 v[144:147], v184
	ds_read_b128 v[148:151], v184 offset:1024
	ds_read_b128 v[180:183], v184 offset:2048
	ds_read_b128 v[184:187], v184 offset:3072
	s_add_u32 s34, s34, 0x100000
	s_addc_u32 s35, s35, 0
	s_mov_b32 m0, s60
	v_lshl_add_u64 v[188:189], s[34:35], 0, v[152:153]
	global_load_lds_dwordx4 v[188:189], off
	v_lshl_add_u64 v[188:189], s[34:35], 0, v[156:157]
	s_mov_b32 m0, s61
	s_nop 0
	global_load_lds_dwordx4 v[188:189], off
	ds_read_b128 v[188:191], v178 offset:32768
	ds_read_b128 v[192:195], v178 offset:33792
	ds_read_b128 v[196:199], v178 offset:34816
	ds_read_b128 v[200:203], v178 offset:35840
	ds_read_b128 v[204:207], v178 offset:36864
	ds_read_b128 v[208:211], v178 offset:37888
	ds_read_b128 v[212:215], v178 offset:38912
	ds_read_b128 v[216:219], v178 offset:39936
	s_waitcnt vmcnt(8)
	s_waitcnt lgkmcnt(0)
	s_barrier
	v_mfma_f32_16x16x32_bf16 v[124:127], v[128:131], v[188:191], v[124:127]
	v_mfma_f32_16x16x32_bf16 v[124:127], v[132:135], v[192:195], v[124:127]
	v_mfma_f32_16x16x32_bf16 v[120:123], v[140:143], v[192:195], v[120:123]
	v_mfma_f32_16x16x32_bf16 v[120:123], v[136:139], v[188:191], v[120:123]
	v_mfma_f32_16x16x32_bf16 v[116:119], v[144:147], v[188:191], v[116:119]
	v_mfma_f32_16x16x32_bf16 v[116:119], v[148:151], v[192:195], v[116:119]
	v_mfma_f32_16x16x32_bf16 v[112:115], v[184:187], v[192:195], v[112:115]
	v_mfma_f32_16x16x32_bf16 v[112:115], v[180:183], v[188:191], v[112:115]
	v_mfma_f32_16x16x32_bf16 v[96:99], v[180:183], v[196:199], v[96:99]
	v_mfma_f32_16x16x32_bf16 v[96:99], v[184:187], v[200:203], v[96:99]
	v_mfma_f32_16x16x32_bf16 v[100:103], v[148:151], v[200:203], v[100:103]
	v_mfma_f32_16x16x32_bf16 v[100:103], v[144:147], v[196:199], v[100:103]
	v_mfma_f32_16x16x32_bf16 v[104:107], v[136:139], v[196:199], v[104:107]
	v_mfma_f32_16x16x32_bf16 v[104:107], v[140:143], v[200:203], v[104:107]
	v_mfma_f32_16x16x32_bf16 v[108:111], v[132:135], v[200:203], v[108:111]
	v_mfma_f32_16x16x32_bf16 v[108:111], v[128:131], v[196:199], v[108:111]
	v_mfma_f32_16x16x32_bf16 v[92:95], v[128:131], v[204:207], v[92:95]
	v_mfma_f32_16x16x32_bf16 v[92:95], v[132:135], v[208:211], v[92:95]
	v_mfma_f32_16x16x32_bf16 v[88:91], v[140:143], v[208:211], v[88:91]
	v_mfma_f32_16x16x32_bf16 v[88:91], v[136:139], v[204:207], v[88:91]
	v_mfma_f32_16x16x32_bf16 v[84:87], v[144:147], v[204:207], v[84:87]
	v_mfma_f32_16x16x32_bf16 v[84:87], v[148:151], v[208:211], v[84:87]
	v_mfma_f32_16x16x32_bf16 v[80:83], v[184:187], v[208:211], v[80:83]
	v_mfma_f32_16x16x32_bf16 v[80:83], v[180:183], v[204:207], v[80:83]
	v_mfma_f32_16x16x32_bf16 v[64:67], v[180:183], v[212:215], v[64:67]
	v_mfma_f32_16x16x32_bf16 v[64:67], v[184:187], v[216:219], v[64:67]
	v_mfma_f32_16x16x32_bf16 v[68:71], v[148:151], v[216:219], v[68:71]
	v_mfma_f32_16x16x32_bf16 v[68:71], v[144:147], v[212:215], v[68:71]
	v_mfma_f32_16x16x32_bf16 v[72:75], v[136:139], v[212:215], v[72:75]
	s_barrier
	s_setprio 3
	v_mfma_f32_16x16x32_bf16 v[72:75], v[140:143], v[216:219], v[72:75]
	v_mfma_f32_16x16x32_bf16 v[76:79], v[132:135], v[216:219], v[76:79]
	v_mfma_f32_16x16x32_bf16 v[76:79], v[128:131], v[212:215], v[76:79]
	s_setprio 0
	s_add_i32 s34, s41, s33
	v_lshl_add_u64 v[172:173], v[172:173], 0, s[16:17]
	s_mov_b32 m0, s34
	s_nop 0
	global_load_lds_dwordx4 v[172:173], off
	s_add_i32 m0, s34, 0x2000
	s_add_u32 s30, s30, 0x100800
	v_lshl_add_u64 v[172:173], v[220:221], 0, s[16:17]
	s_addc_u32 s31, s31, 0
	s_add_i32 s34, s42, s33
	global_load_lds_dwordx4 v[172:173], off
	v_lshl_add_u64 v[172:173], s[30:31], 0, v[154:155]
	s_mov_b32 m0, s34
	s_nop 0
	global_load_lds_dwordx4 v[172:173], off
	v_lshl_add_u64 v[172:173], s[30:31], 0, v[158:159]
	s_add_i32 m0, s34, 0x2000
	s_nop 0
	global_load_lds_dwordx4 v[172:173], off
	v_lshl_add_u64 v[172:173], v[222:223], 0, s[18:19]
	s_mov_b32 m0, s63
	s_nop 0
	global_load_lds_dwordx4 v[172:173], off
	v_lshl_add_u64 v[172:173], v[224:225], 0, s[18:19]
	s_mov_b32 m0, s64
	s_nop 0
	global_load_lds_dwordx4 v[172:173], off
	ds_read_b128 v[188:191], v178 offset:49152
	ds_read_b128 v[192:195], v178 offset:50176
	ds_read_b128 v[196:199], v178 offset:51200
	ds_read_b128 v[200:203], v178 offset:52224
	ds_read_b128 v[204:207], v178 offset:53248
	ds_read_b128 v[208:211], v178 offset:54272
	ds_read_b128 v[212:215], v178 offset:55296
	ds_read_b128 v[216:219], v178 offset:56320
	s_waitcnt vmcnt(8)
	s_waitcnt lgkmcnt(0)
	s_barrier
	v_mfma_f32_16x16x32_bf16 v[60:63], v[128:131], v[188:191], v[60:63]
	v_mfma_f32_16x16x32_bf16 v[60:63], v[132:135], v[192:195], v[60:63]
	v_mfma_f32_16x16x32_bf16 v[56:59], v[140:143], v[192:195], v[56:59]
	v_mfma_f32_16x16x32_bf16 v[56:59], v[136:139], v[188:191], v[56:59]
	v_mfma_f32_16x16x32_bf16 v[52:55], v[144:147], v[188:191], v[52:55]
	v_mfma_f32_16x16x32_bf16 v[52:55], v[148:151], v[192:195], v[52:55]
	v_mfma_f32_16x16x32_bf16 v[48:51], v[184:187], v[192:195], v[48:51]
	v_mfma_f32_16x16x32_bf16 v[48:51], v[180:183], v[188:191], v[48:51]
	v_mfma_f32_16x16x32_bf16 v[32:35], v[180:183], v[196:199], v[32:35]
	v_mfma_f32_16x16x32_bf16 v[32:35], v[184:187], v[200:203], v[32:35]
	v_mfma_f32_16x16x32_bf16 v[36:39], v[148:151], v[200:203], v[36:39]
	v_mfma_f32_16x16x32_bf16 v[36:39], v[144:147], v[196:199], v[36:39]
	v_mfma_f32_16x16x32_bf16 v[40:43], v[136:139], v[196:199], v[40:43]
	v_mfma_f32_16x16x32_bf16 v[40:43], v[140:143], v[200:203], v[40:43]
	v_mfma_f32_16x16x32_bf16 v[44:47], v[132:135], v[200:203], v[44:47]
	v_mfma_f32_16x16x32_bf16 v[44:47], v[128:131], v[196:199], v[44:47]
	v_mfma_f32_16x16x32_bf16 v[28:31], v[128:131], v[204:207], v[28:31]
	v_mfma_f32_16x16x32_bf16 v[28:31], v[132:135], v[208:211], v[28:31]
	v_mfma_f32_16x16x32_bf16 v[24:27], v[140:143], v[208:211], v[24:27]
	v_mfma_f32_16x16x32_bf16 v[24:27], v[136:139], v[204:207], v[24:27]
	v_mfma_f32_16x16x32_bf16 v[20:23], v[144:147], v[204:207], v[20:23]
	v_mfma_f32_16x16x32_bf16 v[20:23], v[148:151], v[208:211], v[20:23]
	v_mfma_f32_16x16x32_bf16 v[16:19], v[184:187], v[208:211], v[16:19]
	v_mfma_f32_16x16x32_bf16 v[16:19], v[180:183], v[204:207], v[16:19]
	v_mfma_f32_16x16x32_bf16 v[0:3], v[180:183], v[212:215], v[0:3]
	v_mfma_f32_16x16x32_bf16 v[0:3], v[184:187], v[216:219], v[0:3]
	v_mfma_f32_16x16x32_bf16 v[4:7], v[148:151], v[216:219], v[4:7]
	v_mfma_f32_16x16x32_bf16 v[4:7], v[144:147], v[212:215], v[4:7]
	v_mfma_f32_16x16x32_bf16 v[8:11], v[136:139], v[212:215], v[8:11]
	s_barrier
	s_setprio 3
	v_mfma_f32_16x16x32_bf16 v[8:11], v[140:143], v[216:219], v[8:11]
	v_mfma_f32_16x16x32_bf16 v[12:15], v[132:135], v[216:219], v[12:15]
	v_mfma_f32_16x16x32_bf16 v[12:15], v[128:131], v[212:215], v[12:15]
	s_setprio 0
	s_add_i32 s40, s40, 2
	s_add_u32 s38, s38, 0x1000
	s_addc_u32 s39, s39, 0
	s_add_u32 s28, s28, 0x100
	s_addc_u32 s29, s29, 0
	s_cmp_gt_u32 s40, 61
	s_cbranch_scc0 .LBB0_1202

.LBB0_1263:
	ds_read_b128 v[146:149], v152
	ds_read_b128 v[156:159], v152 offset:1024
	ds_read_b128 v[160:163], v152 offset:2048
	ds_read_b128 v[164:167], v152 offset:3072
	ds_read_b128 v[168:171], v153
	ds_read_b128 v[172:175], v153 offset:1024
	ds_read_b128 v[176:179], v153 offset:2048
	ds_read_b128 v[180:183], v153 offset:3072
	s_add_u32 s22, s20, 0x100
	s_addc_u32 s23, s21, 0
	s_cmp_eq_u32 s46, 12
	s_cselect_b32 s27, s5, s23
	s_cselect_b32 s26, s4, s22
	s_cselect_b32 s25, s19, s15
	s_cselect_b32 s24, s18, s6
	v_lshl_add_u64 v[184:185], s[20:21], 0, v[136:137]
	s_add_i32 m0, s17, 0xc000
	s_nop 0
	global_load_lds_dwordx4 v[184:185], off
	v_lshl_add_u64 v[184:185], s[20:21], 0, v[138:139]
	s_add_i32 m0, s17, 0xe000
	s_nop 0
	global_load_lds_dwordx4 v[184:185], off
	ds_read_b128 v[184:187], v154
	ds_read_b128 v[188:191], v154 offset:1024
	ds_read_b128 v[192:195], v154 offset:2048
	ds_read_b128 v[196:199], v154 offset:3072
	ds_read_b128 v[200:203], v154 offset:4096
	ds_read_b128 v[204:207], v154 offset:5120
	ds_read_b128 v[208:211], v154 offset:6144
	ds_read_b128 v[212:215], v154 offset:7168
	s_waitcnt vmcnt(8)
	s_waitcnt lgkmcnt(0)
	s_barrier
	v_mfma_f32_16x16x32_bf16 v[124:127], v[146:149], v[184:187], v[124:127]
	v_mfma_f32_16x16x32_bf16 v[124:127], v[156:159], v[188:191], v[124:127]
	v_mfma_f32_16x16x32_bf16 v[120:123], v[164:167], v[188:191], v[120:123]
	v_mfma_f32_16x16x32_bf16 v[120:123], v[160:163], v[184:187], v[120:123]
	v_mfma_f32_16x16x32_bf16 v[116:119], v[168:171], v[184:187], v[116:119]
	v_mfma_f32_16x16x32_bf16 v[116:119], v[172:175], v[188:191], v[116:119]
	v_mfma_f32_16x16x32_bf16 v[108:111], v[180:183], v[188:191], v[108:111]
	v_mfma_f32_16x16x32_bf16 v[108:111], v[176:179], v[184:187], v[108:111]
	v_mfma_f32_16x16x32_bf16 v[92:95], v[176:179], v[192:195], v[92:95]
	v_mfma_f32_16x16x32_bf16 v[92:95], v[180:183], v[196:199], v[92:95]
	v_mfma_f32_16x16x32_bf16 v[100:103], v[172:175], v[196:199], v[100:103]
	v_mfma_f32_16x16x32_bf16 v[100:103], v[168:171], v[192:195], v[100:103]
	v_mfma_f32_16x16x32_bf16 v[104:107], v[160:163], v[192:195], v[104:107]
	v_mfma_f32_16x16x32_bf16 v[104:107], v[164:167], v[196:199], v[104:107]
	v_mfma_f32_16x16x32_bf16 v[112:115], v[156:159], v[196:199], v[112:115]
	v_mfma_f32_16x16x32_bf16 v[112:115], v[146:149], v[192:195], v[112:115]
	v_mfma_f32_16x16x32_bf16 v[96:99], v[146:149], v[200:203], v[96:99]
	v_mfma_f32_16x16x32_bf16 v[96:99], v[156:159], v[204:207], v[96:99]
	v_mfma_f32_16x16x32_bf16 v[88:91], v[164:167], v[204:207], v[88:91]
	v_mfma_f32_16x16x32_bf16 v[88:91], v[160:163], v[200:203], v[88:91]
	v_mfma_f32_16x16x32_bf16 v[84:87], v[168:171], v[200:203], v[84:87]
	v_mfma_f32_16x16x32_bf16 v[84:87], v[172:175], v[204:207], v[84:87]
	v_mfma_f32_16x16x32_bf16 v[76:79], v[180:183], v[204:207], v[76:79]
	v_mfma_f32_16x16x32_bf16 v[76:79], v[176:179], v[200:203], v[76:79]
	v_mfma_f32_16x16x32_bf16 v[64:67], v[176:179], v[208:211], v[64:67]
	v_mfma_f32_16x16x32_bf16 v[64:67], v[180:183], v[212:215], v[64:67]
	v_mfma_f32_16x16x32_bf16 v[68:71], v[172:175], v[212:215], v[68:71]
	v_mfma_f32_16x16x32_bf16 v[68:71], v[168:171], v[208:211], v[68:71]
	v_mfma_f32_16x16x32_bf16 v[72:75], v[160:163], v[208:211], v[72:75]
	s_barrier
	s_setprio 3
	v_mfma_f32_16x16x32_bf16 v[72:75], v[164:167], v[212:215], v[72:75]
	v_mfma_f32_16x16x32_bf16 v[80:83], v[156:159], v[212:215], v[80:83]
	v_mfma_f32_16x16x32_bf16 v[80:83], v[146:149], v[208:211], v[80:83]
	s_setprio 0
	s_add_i32 s20, s41, s33
	v_lshl_add_u64 v[216:217], s[24:25], 0, v[130:131]
	s_mov_b32 m0, s20
	v_lshl_add_u64 v[218:219], s[24:25], 0, v[134:135]
	global_load_lds_dwordx4 v[216:217], off
	s_add_i32 m0, s20, 0x2000
	s_add_u32 s20, s24, 0x200000
	s_addc_u32 s21, s25, 0
	s_add_i32 s47, s42, s33
	global_load_lds_dwordx4 v[218:219], off
	v_lshl_add_u64 v[184:185], s[20:21], 0, v[130:131]
	s_mov_b32 m0, s47
	v_lshl_add_u64 v[220:221], s[26:27], 0, v[128:129]
	global_load_lds_dwordx4 v[184:185], off
	v_lshl_add_u64 v[184:185], s[20:21], 0, v[134:135]
	s_add_i32 m0, s47, 0x2000
	v_lshl_add_u64 v[222:223], s[26:27], 0, v[132:133]
	global_load_lds_dwordx4 v[184:185], off
	s_mov_b32 m0, s17
	s_nop 0
	global_load_lds_dwordx4 v[220:221], off
	s_mov_b32 m0, s34
	s_nop 0
	global_load_lds_dwordx4 v[222:223], off
	ds_read_b128 v[184:187], v154 offset:16384
	ds_read_b128 v[188:191], v154 offset:17408
	ds_read_b128 v[192:195], v154 offset:18432
	ds_read_b128 v[196:199], v154 offset:19456
	ds_read_b128 v[200:203], v154 offset:20480
	ds_read_b128 v[204:207], v154 offset:21504
	ds_read_b128 v[208:211], v154 offset:22528
	ds_read_b128 v[212:215], v154 offset:23552
	s_waitcnt vmcnt(8)
	s_waitcnt lgkmcnt(0)
	s_barrier
	v_mfma_f32_16x16x32_bf16 v[60:63], v[146:149], v[184:187], v[60:63]
	v_mfma_f32_16x16x32_bf16 v[60:63], v[156:159], v[188:191], v[60:63]
	v_mfma_f32_16x16x32_bf16 v[56:59], v[164:167], v[188:191], v[56:59]
	v_mfma_f32_16x16x32_bf16 v[56:59], v[160:163], v[184:187], v[56:59]
	v_mfma_f32_16x16x32_bf16 v[52:55], v[168:171], v[184:187], v[52:55]
	v_mfma_f32_16x16x32_bf16 v[52:55], v[172:175], v[188:191], v[52:55]
	v_mfma_f32_16x16x32_bf16 v[44:47], v[180:183], v[188:191], v[44:47]
	v_mfma_f32_16x16x32_bf16 v[44:47], v[176:179], v[184:187], v[44:47]
	v_mfma_f32_16x16x32_bf16 v[28:31], v[176:179], v[192:195], v[28:31]
	v_mfma_f32_16x16x32_bf16 v[28:31], v[180:183], v[196:199], v[28:31]
	v_mfma_f32_16x16x32_bf16 v[36:39], v[172:175], v[196:199], v[36:39]
	v_mfma_f32_16x16x32_bf16 v[36:39], v[168:171], v[192:195], v[36:39]
	v_mfma_f32_16x16x32_bf16 v[40:43], v[160:163], v[192:195], v[40:43]
	v_mfma_f32_16x16x32_bf16 v[40:43], v[164:167], v[196:199], v[40:43]
	v_mfma_f32_16x16x32_bf16 v[48:51], v[156:159], v[196:199], v[48:51]
	v_mfma_f32_16x16x32_bf16 v[48:51], v[146:149], v[192:195], v[48:51]
	v_mfma_f32_16x16x32_bf16 v[32:35], v[146:149], v[200:203], v[32:35]
	v_mfma_f32_16x16x32_bf16 v[32:35], v[156:159], v[204:207], v[32:35]
	v_mfma_f32_16x16x32_bf16 v[24:27], v[164:167], v[204:207], v[24:27]
	v_mfma_f32_16x16x32_bf16 v[24:27], v[160:163], v[200:203], v[24:27]
	v_mfma_f32_16x16x32_bf16 v[20:23], v[168:171], v[200:203], v[20:23]
	v_mfma_f32_16x16x32_bf16 v[20:23], v[172:175], v[204:207], v[20:23]
	v_mfma_f32_16x16x32_bf16 v[12:15], v[180:183], v[204:207], v[12:15]
	v_mfma_f32_16x16x32_bf16 v[12:15], v[176:179], v[200:203], v[12:15]
	v_mfma_f32_16x16x32_bf16 v[0:3], v[176:179], v[208:211], v[0:3]
	v_mfma_f32_16x16x32_bf16 v[0:3], v[180:183], v[212:215], v[0:3]
	v_mfma_f32_16x16x32_bf16 v[4:7], v[172:175], v[212:215], v[4:7]
	v_mfma_f32_16x16x32_bf16 v[4:7], v[168:171], v[208:211], v[4:7]
	v_mfma_f32_16x16x32_bf16 v[8:11], v[160:163], v[208:211], v[8:11]
	s_barrier
	s_setprio 3
	v_mfma_f32_16x16x32_bf16 v[8:11], v[164:167], v[212:215], v[8:11]
	v_mfma_f32_16x16x32_bf16 v[16:19], v[156:159], v[212:215], v[16:19]
	v_mfma_f32_16x16x32_bf16 v[16:19], v[146:149], v[208:211], v[16:19]
	s_setprio 0
	s_add_i32 s47, 0, 0x18000
	v_add_u32_e32 v144, s47, v145
	s_add_i32 s48, 0, 0x1c000
	ds_read_b128 v[146:149], v144
	ds_read_b128 v[156:159], v144 offset:1024
	ds_read_b128 v[160:163], v144 offset:2048
	ds_read_b128 v[164:167], v144 offset:3072
	v_add_u32_e32 v144, s48, v145
	ds_read_b128 v[168:171], v144
	ds_read_b128 v[172:175], v144 offset:1024
	ds_read_b128 v[176:179], v144 offset:2048
	ds_read_b128 v[180:183], v144 offset:3072
	s_add_u32 s20, s26, 0x200000
	s_addc_u32 s21, s27, 0
	s_mov_b32 m0, s35
	v_lshl_add_u64 v[184:185], s[20:21], 0, v[128:129]
	global_load_lds_dwordx4 v[184:185], off
	v_lshl_add_u64 v[184:185], s[20:21], 0, v[132:133]
	s_mov_b32 m0, s36
	s_nop 0
	global_load_lds_dwordx4 v[184:185], off
	ds_read_b128 v[184:187], v154 offset:32768
	ds_read_b128 v[188:191], v154 offset:33792
	ds_read_b128 v[192:195], v154 offset:34816
	ds_read_b128 v[196:199], v154 offset:35840
	ds_read_b128 v[200:203], v154 offset:36864
	ds_read_b128 v[204:207], v154 offset:37888
	ds_read_b128 v[208:211], v154 offset:38912
	ds_read_b128 v[212:215], v154 offset:39936
	s_waitcnt vmcnt(8)
	s_waitcnt lgkmcnt(0)
	s_barrier
	v_mfma_f32_16x16x32_bf16 v[124:127], v[146:149], v[184:187], v[124:127]
	v_mfma_f32_16x16x32_bf16 v[124:127], v[156:159], v[188:191], v[124:127]
	v_mfma_f32_16x16x32_bf16 v[120:123], v[164:167], v[188:191], v[120:123]
	v_mfma_f32_16x16x32_bf16 v[120:123], v[160:163], v[184:187], v[120:123]
	v_mfma_f32_16x16x32_bf16 v[116:119], v[168:171], v[184:187], v[116:119]
	v_mfma_f32_16x16x32_bf16 v[116:119], v[172:175], v[188:191], v[116:119]
	v_mfma_f32_16x16x32_bf16 v[108:111], v[180:183], v[188:191], v[108:111]
	v_mfma_f32_16x16x32_bf16 v[108:111], v[176:179], v[184:187], v[108:111]
	v_mfma_f32_16x16x32_bf16 v[92:95], v[176:179], v[192:195], v[92:95]
	v_mfma_f32_16x16x32_bf16 v[92:95], v[180:183], v[196:199], v[92:95]
	v_mfma_f32_16x16x32_bf16 v[100:103], v[172:175], v[196:199], v[100:103]
	v_mfma_f32_16x16x32_bf16 v[100:103], v[168:171], v[192:195], v[100:103]
	v_mfma_f32_16x16x32_bf16 v[104:107], v[160:163], v[192:195], v[104:107]
	v_mfma_f32_16x16x32_bf16 v[104:107], v[164:167], v[196:199], v[104:107]
	v_mfma_f32_16x16x32_bf16 v[112:115], v[156:159], v[196:199], v[112:115]
	v_mfma_f32_16x16x32_bf16 v[112:115], v[146:149], v[192:195], v[112:115]
	v_mfma_f32_16x16x32_bf16 v[96:99], v[146:149], v[200:203], v[96:99]
	v_mfma_f32_16x16x32_bf16 v[96:99], v[156:159], v[204:207], v[96:99]
	v_mfma_f32_16x16x32_bf16 v[88:91], v[164:167], v[204:207], v[88:91]
	v_mfma_f32_16x16x32_bf16 v[88:91], v[160:163], v[200:203], v[88:91]
	v_mfma_f32_16x16x32_bf16 v[84:87], v[168:171], v[200:203], v[84:87]
	v_mfma_f32_16x16x32_bf16 v[84:87], v[172:175], v[204:207], v[84:87]
	v_mfma_f32_16x16x32_bf16 v[76:79], v[180:183], v[204:207], v[76:79]
	v_mfma_f32_16x16x32_bf16 v[76:79], v[176:179], v[200:203], v[76:79]
	v_mfma_f32_16x16x32_bf16 v[64:67], v[176:179], v[208:211], v[64:67]
	v_mfma_f32_16x16x32_bf16 v[64:67], v[180:183], v[212:215], v[64:67]
	v_mfma_f32_16x16x32_bf16 v[68:71], v[172:175], v[212:215], v[68:71]
	v_mfma_f32_16x16x32_bf16 v[68:71], v[168:171], v[208:211], v[68:71]
	v_mfma_f32_16x16x32_bf16 v[72:75], v[160:163], v[208:211], v[72:75]
	s_barrier
	s_setprio 3
	v_mfma_f32_16x16x32_bf16 v[72:75], v[164:167], v[212:215], v[72:75]
	v_mfma_f32_16x16x32_bf16 v[80:83], v[156:159], v[212:215], v[80:83]
	v_mfma_f32_16x16x32_bf16 v[80:83], v[146:149], v[208:211], v[80:83]
	s_setprio 0
	s_add_i32 s20, s47, s33
	v_lshl_add_u64 v[184:185], v[216:217], 0, s[12:13]
	s_mov_b32 m0, s20
	s_nop 0
	global_load_lds_dwordx4 v[184:185], off
	s_add_i32 m0, s20, 0x2000
	s_add_u32 s20, s24, 0x200080
	v_lshl_add_u64 v[184:185], v[218:219], 0, s[12:13]
	s_addc_u32 s21, s25, 0
	s_add_i32 s24, s48, s33
	global_load_lds_dwordx4 v[184:185], off
	v_lshl_add_u64 v[184:185], s[20:21], 0, v[130:131]
	s_mov_b32 m0, s24
	s_nop 0
	global_load_lds_dwordx4 v[184:185], off
	v_lshl_add_u64 v[184:185], s[20:21], 0, v[134:135]
	s_add_i32 m0, s24, 0x2000
	s_nop 0
	global_load_lds_dwordx4 v[184:185], off
	v_lshl_add_u64 v[184:185], v[220:221], 0, s[12:13]
	s_mov_b32 m0, s37
	s_nop 0
	global_load_lds_dwordx4 v[184:185], off
	v_lshl_add_u64 v[184:185], v[222:223], 0, s[12:13]
	s_mov_b32 m0, s38
	s_nop 0
	global_load_lds_dwordx4 v[184:185], off
	ds_read_b128 v[184:187], v154 offset:49152
	ds_read_b128 v[188:191], v154 offset:50176
	ds_read_b128 v[192:195], v154 offset:51200
	ds_read_b128 v[196:199], v154 offset:52224
	ds_read_b128 v[200:203], v154 offset:53248
	ds_read_b128 v[204:207], v154 offset:54272
	ds_read_b128 v[208:211], v154 offset:55296
	ds_read_b128 v[212:215], v154 offset:56320
	s_waitcnt vmcnt(8)
	s_waitcnt lgkmcnt(0)
	s_barrier
	v_mfma_f32_16x16x32_bf16 v[60:63], v[146:149], v[184:187], v[60:63]
	v_mfma_f32_16x16x32_bf16 v[60:63], v[156:159], v[188:191], v[60:63]
	v_mfma_f32_16x16x32_bf16 v[56:59], v[164:167], v[188:191], v[56:59]
	v_mfma_f32_16x16x32_bf16 v[56:59], v[160:163], v[184:187], v[56:59]
	v_mfma_f32_16x16x32_bf16 v[52:55], v[168:171], v[184:187], v[52:55]
	v_mfma_f32_16x16x32_bf16 v[52:55], v[172:175], v[188:191], v[52:55]
	v_mfma_f32_16x16x32_bf16 v[44:47], v[180:183], v[188:191], v[44:47]
	v_mfma_f32_16x16x32_bf16 v[44:47], v[176:179], v[184:187], v[44:47]
	v_mfma_f32_16x16x32_bf16 v[28:31], v[176:179], v[192:195], v[28:31]
	v_mfma_f32_16x16x32_bf16 v[28:31], v[180:183], v[196:199], v[28:31]
	v_mfma_f32_16x16x32_bf16 v[36:39], v[172:175], v[196:199], v[36:39]
	v_mfma_f32_16x16x32_bf16 v[36:39], v[168:171], v[192:195], v[36:39]
	v_mfma_f32_16x16x32_bf16 v[40:43], v[160:163], v[192:195], v[40:43]
	v_mfma_f32_16x16x32_bf16 v[40:43], v[164:167], v[196:199], v[40:43]
	v_mfma_f32_16x16x32_bf16 v[48:51], v[156:159], v[196:199], v[48:51]
	v_mfma_f32_16x16x32_bf16 v[48:51], v[146:149], v[192:195], v[48:51]
	v_mfma_f32_16x16x32_bf16 v[32:35], v[146:149], v[200:203], v[32:35]
	v_mfma_f32_16x16x32_bf16 v[32:35], v[156:159], v[204:207], v[32:35]
	v_mfma_f32_16x16x32_bf16 v[24:27], v[164:167], v[204:207], v[24:27]
	v_mfma_f32_16x16x32_bf16 v[24:27], v[160:163], v[200:203], v[24:27]
	v_mfma_f32_16x16x32_bf16 v[20:23], v[168:171], v[200:203], v[20:23]
	v_mfma_f32_16x16x32_bf16 v[20:23], v[172:175], v[204:207], v[20:23]
	v_mfma_f32_16x16x32_bf16 v[12:15], v[180:183], v[204:207], v[12:15]
	v_mfma_f32_16x16x32_bf16 v[12:15], v[176:179], v[200:203], v[12:15]
	v_mfma_f32_16x16x32_bf16 v[0:3], v[176:179], v[208:211], v[0:3]
	v_mfma_f32_16x16x32_bf16 v[0:3], v[180:183], v[212:215], v[0:3]
	v_mfma_f32_16x16x32_bf16 v[4:7], v[172:175], v[212:215], v[4:7]
	v_mfma_f32_16x16x32_bf16 v[4:7], v[168:171], v[208:211], v[4:7]
	v_mfma_f32_16x16x32_bf16 v[8:11], v[160:163], v[208:211], v[8:11]
	s_barrier
	s_setprio 3
	v_mfma_f32_16x16x32_bf16 v[8:11], v[164:167], v[212:215], v[8:11]
	v_mfma_f32_16x16x32_bf16 v[16:19], v[156:159], v[212:215], v[16:19]
	v_mfma_f32_16x16x32_bf16 v[16:19], v[146:149], v[208:211], v[16:19]
	s_setprio 0
	s_add_i32 s46, s46, 2
	s_add_u32 s6, s6, 0x100
	s_addc_u32 s15, s15, 0
	s_cmp_gt_u32 s46, 13
	s_mov_b64 s[20:21], s[22:23]
	s_cbranch_scc0 .LBB0_1263
	s_and_b64 vcc, exec, s[8:9]
	s_cbranch_vccz .LBB0_1266
	s_barrier

.LBB0_1340:
	v_add_u32_e32 v166, s51, v152
	v_add_u32_e32 v182, s52, v152
	ds_read_b128 v[154:157], v166
	ds_read_b128 v[158:161], v166 offset:1024
	ds_read_b128 v[162:165], v166 offset:2048
	ds_read_b128 v[166:169], v166 offset:3072
	ds_read_b128 v[170:173], v182
	ds_read_b128 v[174:177], v182 offset:1024
	ds_read_b128 v[178:181], v182 offset:2048
	ds_read_b128 v[182:185], v182 offset:3072
	s_add_u32 s30, s10, s28
	s_addc_u32 s31, s11, s29
	s_cmp_eq_u32 s58, 60
	s_cselect_b32 s35, s23, s31
	s_cselect_b32 s34, s54, s30
	s_cselect_b32 s31, s21, s57
	s_cselect_b32 s30, s55, s56
	v_lshl_add_u64 v[186:187], s[10:11], 0, v[146:147]
	s_add_i32 m0, s44, 0xc000
	s_nop 0
	global_load_lds_dwordx4 v[186:187], off
	v_lshl_add_u64 v[186:187], s[10:11], 0, v[144:145]
	s_add_i32 m0, s44, 0xe000
	s_nop 0
	global_load_lds_dwordx4 v[186:187], off
	ds_read_b128 v[186:189], v153
	ds_read_b128 v[190:193], v153 offset:1024
	ds_read_b128 v[194:197], v153 offset:2048
	ds_read_b128 v[198:201], v153 offset:3072
	ds_read_b128 v[202:205], v153 offset:4096
	ds_read_b128 v[206:209], v153 offset:5120
	ds_read_b128 v[210:213], v153 offset:6144
	ds_read_b128 v[214:217], v153 offset:7168
	s_waitcnt vmcnt(8)
	s_waitcnt lgkmcnt(0)
	s_barrier
	v_mfma_f32_16x16x32_bf16 v[124:127], v[154:157], v[186:189], v[124:127]
	v_mfma_f32_16x16x32_bf16 v[124:127], v[158:161], v[190:193], v[124:127]
	v_mfma_f32_16x16x32_bf16 v[120:123], v[166:169], v[190:193], v[120:123]
	v_mfma_f32_16x16x32_bf16 v[120:123], v[162:165], v[186:189], v[120:123]
	v_mfma_f32_16x16x32_bf16 v[116:119], v[170:173], v[186:189], v[116:119]
	v_mfma_f32_16x16x32_bf16 v[116:119], v[174:177], v[190:193], v[116:119]
	v_mfma_f32_16x16x32_bf16 v[112:115], v[182:185], v[190:193], v[112:115]
	v_mfma_f32_16x16x32_bf16 v[112:115], v[178:181], v[186:189], v[112:115]
	v_mfma_f32_16x16x32_bf16 v[96:99], v[178:181], v[194:197], v[96:99]
	v_mfma_f32_16x16x32_bf16 v[96:99], v[182:185], v[198:201], v[96:99]
	v_mfma_f32_16x16x32_bf16 v[100:103], v[174:177], v[198:201], v[100:103]
	v_mfma_f32_16x16x32_bf16 v[100:103], v[170:173], v[194:197], v[100:103]
	v_mfma_f32_16x16x32_bf16 v[104:107], v[162:165], v[194:197], v[104:107]
	v_mfma_f32_16x16x32_bf16 v[104:107], v[166:169], v[198:201], v[104:107]
	v_mfma_f32_16x16x32_bf16 v[108:111], v[158:161], v[198:201], v[108:111]
	v_mfma_f32_16x16x32_bf16 v[108:111], v[154:157], v[194:197], v[108:111]
	v_mfma_f32_16x16x32_bf16 v[92:95], v[154:157], v[202:205], v[92:95]
	v_mfma_f32_16x16x32_bf16 v[92:95], v[158:161], v[206:209], v[92:95]
	v_mfma_f32_16x16x32_bf16 v[88:91], v[166:169], v[206:209], v[88:91]
	v_mfma_f32_16x16x32_bf16 v[88:91], v[162:165], v[202:205], v[88:91]
	v_mfma_f32_16x16x32_bf16 v[84:87], v[170:173], v[202:205], v[84:87]
	v_mfma_f32_16x16x32_bf16 v[84:87], v[174:177], v[206:209], v[84:87]
	v_mfma_f32_16x16x32_bf16 v[80:83], v[182:185], v[206:209], v[80:83]
	v_mfma_f32_16x16x32_bf16 v[80:83], v[178:181], v[202:205], v[80:83]
	v_mfma_f32_16x16x32_bf16 v[64:67], v[178:181], v[210:213], v[64:67]
	v_mfma_f32_16x16x32_bf16 v[64:67], v[182:185], v[214:217], v[64:67]
	v_mfma_f32_16x16x32_bf16 v[68:71], v[174:177], v[214:217], v[68:71]
	v_mfma_f32_16x16x32_bf16 v[68:71], v[170:173], v[210:213], v[68:71]
	v_mfma_f32_16x16x32_bf16 v[72:75], v[162:165], v[210:213], v[72:75]
	s_barrier
	s_setprio 3
	v_mfma_f32_16x16x32_bf16 v[72:75], v[166:169], v[214:217], v[72:75]
	v_mfma_f32_16x16x32_bf16 v[76:79], v[158:161], v[214:217], v[76:79]
	v_mfma_f32_16x16x32_bf16 v[76:79], v[154:157], v[210:213], v[76:79]
	s_setprio 0
	s_add_i32 s59, s51, s43
	v_lshl_add_u64 v[218:219], s[30:31], 0, v[130:131]
	s_mov_b32 m0, s59
	v_lshl_add_u64 v[220:221], s[30:31], 0, v[134:135]
	global_load_lds_dwordx4 v[218:219], off
	s_add_i32 m0, s59, 0x2000
	s_add_u32 s60, s30, 0x100000
	s_addc_u32 s61, s31, 0
	s_add_i32 s59, s52, s43
	global_load_lds_dwordx4 v[220:221], off
	v_lshl_add_u64 v[186:187], s[60:61], 0, v[130:131]
	s_mov_b32 m0, s59
	v_lshl_add_u64 v[222:223], s[34:35], 0, v[128:129]
	global_load_lds_dwordx4 v[186:187], off
	v_lshl_add_u64 v[186:187], s[60:61], 0, v[134:135]
	s_add_i32 m0, s59, 0x2000
	v_lshl_add_u64 v[224:225], s[34:35], 0, v[132:133]
	global_load_lds_dwordx4 v[186:187], off
	s_mov_b32 m0, s44
	s_nop 0
	global_load_lds_dwordx4 v[222:223], off
	s_mov_b32 m0, s45
	s_nop 0
	global_load_lds_dwordx4 v[224:225], off
	ds_read_b128 v[186:189], v153 offset:16384
	ds_read_b128 v[190:193], v153 offset:17408
	ds_read_b128 v[194:197], v153 offset:18432
	ds_read_b128 v[198:201], v153 offset:19456
	ds_read_b128 v[202:205], v153 offset:20480
	ds_read_b128 v[206:209], v153 offset:21504
	ds_read_b128 v[210:213], v153 offset:22528
	ds_read_b128 v[214:217], v153 offset:23552
	s_waitcnt vmcnt(8)
	s_waitcnt lgkmcnt(0)
	s_barrier
	v_mfma_f32_16x16x32_bf16 v[60:63], v[154:157], v[186:189], v[60:63]
	v_mfma_f32_16x16x32_bf16 v[60:63], v[158:161], v[190:193], v[60:63]
	v_mfma_f32_16x16x32_bf16 v[56:59], v[166:169], v[190:193], v[56:59]
	v_mfma_f32_16x16x32_bf16 v[56:59], v[162:165], v[186:189], v[56:59]
	v_mfma_f32_16x16x32_bf16 v[52:55], v[170:173], v[186:189], v[52:55]
	v_mfma_f32_16x16x32_bf16 v[52:55], v[174:177], v[190:193], v[52:55]
	v_mfma_f32_16x16x32_bf16 v[48:51], v[182:185], v[190:193], v[48:51]
	v_mfma_f32_16x16x32_bf16 v[48:51], v[178:181], v[186:189], v[48:51]
	v_mfma_f32_16x16x32_bf16 v[32:35], v[178:181], v[194:197], v[32:35]
	v_mfma_f32_16x16x32_bf16 v[32:35], v[182:185], v[198:201], v[32:35]
	v_mfma_f32_16x16x32_bf16 v[36:39], v[174:177], v[198:201], v[36:39]
	v_mfma_f32_16x16x32_bf16 v[36:39], v[170:173], v[194:197], v[36:39]
	v_mfma_f32_16x16x32_bf16 v[40:43], v[162:165], v[194:197], v[40:43]
	v_mfma_f32_16x16x32_bf16 v[40:43], v[166:169], v[198:201], v[40:43]
	v_mfma_f32_16x16x32_bf16 v[44:47], v[158:161], v[198:201], v[44:47]
	v_mfma_f32_16x16x32_bf16 v[44:47], v[154:157], v[194:197], v[44:47]
	v_mfma_f32_16x16x32_bf16 v[28:31], v[154:157], v[202:205], v[28:31]
	v_mfma_f32_16x16x32_bf16 v[28:31], v[158:161], v[206:209], v[28:31]
	v_mfma_f32_16x16x32_bf16 v[24:27], v[166:169], v[206:209], v[24:27]
	v_mfma_f32_16x16x32_bf16 v[24:27], v[162:165], v[202:205], v[24:27]
	v_mfma_f32_16x16x32_bf16 v[20:23], v[170:173], v[202:205], v[20:23]
	v_mfma_f32_16x16x32_bf16 v[20:23], v[174:177], v[206:209], v[20:23]
	v_mfma_f32_16x16x32_bf16 v[16:19], v[182:185], v[206:209], v[16:19]
	v_mfma_f32_16x16x32_bf16 v[16:19], v[178:181], v[202:205], v[16:19]
	v_mfma_f32_16x16x32_bf16 v[0:3], v[178:181], v[210:213], v[0:3]
	v_mfma_f32_16x16x32_bf16 v[0:3], v[182:185], v[214:217], v[0:3]
	v_mfma_f32_16x16x32_bf16 v[4:7], v[174:177], v[214:217], v[4:7]
	v_mfma_f32_16x16x32_bf16 v[4:7], v[170:173], v[210:213], v[4:7]
	v_mfma_f32_16x16x32_bf16 v[8:11], v[162:165], v[210:213], v[8:11]
	s_barrier
	s_setprio 3
	v_mfma_f32_16x16x32_bf16 v[8:11], v[166:169], v[214:217], v[8:11]
	v_mfma_f32_16x16x32_bf16 v[12:15], v[158:161], v[214:217], v[12:15]
	v_mfma_f32_16x16x32_bf16 v[12:15], v[154:157], v[210:213], v[12:15]
	s_setprio 0
	s_add_i32 s59, 0, 0x18000
	s_add_i32 s60, 0, 0x1c000
	v_add_u32_e32 v166, s59, v152
	v_add_u32_e32 v182, s60, v152
	ds_read_b128 v[154:157], v166
	ds_read_b128 v[158:161], v166 offset:1024
	ds_read_b128 v[162:165], v166 offset:2048
	ds_read_b128 v[166:169], v166 offset:3072
	ds_read_b128 v[170:173], v182
	ds_read_b128 v[174:177], v182 offset:1024
	ds_read_b128 v[178:181], v182 offset:2048
	ds_read_b128 v[182:185], v182 offset:3072
	s_add_u32 s34, s34, 0x100000
	s_addc_u32 s35, s35, 0
	s_mov_b32 m0, s46
	v_lshl_add_u64 v[186:187], s[34:35], 0, v[128:129]
	global_load_lds_dwordx4 v[186:187], off
	v_lshl_add_u64 v[186:187], s[34:35], 0, v[132:133]
	s_mov_b32 m0, s47
	s_nop 0
	global_load_lds_dwordx4 v[186:187], off
	ds_read_b128 v[186:189], v153 offset:32768
	ds_read_b128 v[190:193], v153 offset:33792
	ds_read_b128 v[194:197], v153 offset:34816
	ds_read_b128 v[198:201], v153 offset:35840
	ds_read_b128 v[202:205], v153 offset:36864
	ds_read_b128 v[206:209], v153 offset:37888
	ds_read_b128 v[210:213], v153 offset:38912
	ds_read_b128 v[214:217], v153 offset:39936
	s_waitcnt vmcnt(8)
	s_waitcnt lgkmcnt(0)
	s_barrier
	v_mfma_f32_16x16x32_bf16 v[124:127], v[154:157], v[186:189], v[124:127]
	v_mfma_f32_16x16x32_bf16 v[124:127], v[158:161], v[190:193], v[124:127]
	v_mfma_f32_16x16x32_bf16 v[120:123], v[166:169], v[190:193], v[120:123]
	v_mfma_f32_16x16x32_bf16 v[120:123], v[162:165], v[186:189], v[120:123]
	v_mfma_f32_16x16x32_bf16 v[116:119], v[170:173], v[186:189], v[116:119]
	v_mfma_f32_16x16x32_bf16 v[116:119], v[174:177], v[190:193], v[116:119]
	v_mfma_f32_16x16x32_bf16 v[112:115], v[182:185], v[190:193], v[112:115]
	v_mfma_f32_16x16x32_bf16 v[112:115], v[178:181], v[186:189], v[112:115]
	v_mfma_f32_16x16x32_bf16 v[96:99], v[178:181], v[194:197], v[96:99]
	v_mfma_f32_16x16x32_bf16 v[96:99], v[182:185], v[198:201], v[96:99]
	v_mfma_f32_16x16x32_bf16 v[100:103], v[174:177], v[198:201], v[100:103]
	v_mfma_f32_16x16x32_bf16 v[100:103], v[170:173], v[194:197], v[100:103]
	v_mfma_f32_16x16x32_bf16 v[104:107], v[162:165], v[194:197], v[104:107]
	v_mfma_f32_16x16x32_bf16 v[104:107], v[166:169], v[198:201], v[104:107]
	v_mfma_f32_16x16x32_bf16 v[108:111], v[158:161], v[198:201], v[108:111]
	v_mfma_f32_16x16x32_bf16 v[108:111], v[154:157], v[194:197], v[108:111]
	v_mfma_f32_16x16x32_bf16 v[92:95], v[154:157], v[202:205], v[92:95]
	v_mfma_f32_16x16x32_bf16 v[92:95], v[158:161], v[206:209], v[92:95]
	v_mfma_f32_16x16x32_bf16 v[88:91], v[166:169], v[206:209], v[88:91]
	v_mfma_f32_16x16x32_bf16 v[88:91], v[162:165], v[202:205], v[88:91]
	v_mfma_f32_16x16x32_bf16 v[84:87], v[170:173], v[202:205], v[84:87]
	v_mfma_f32_16x16x32_bf16 v[84:87], v[174:177], v[206:209], v[84:87]
	v_mfma_f32_16x16x32_bf16 v[80:83], v[182:185], v[206:209], v[80:83]
	v_mfma_f32_16x16x32_bf16 v[80:83], v[178:181], v[202:205], v[80:83]
	v_mfma_f32_16x16x32_bf16 v[64:67], v[178:181], v[210:213], v[64:67]
	v_mfma_f32_16x16x32_bf16 v[64:67], v[182:185], v[214:217], v[64:67]
	v_mfma_f32_16x16x32_bf16 v[68:71], v[174:177], v[214:217], v[68:71]
	v_mfma_f32_16x16x32_bf16 v[68:71], v[170:173], v[210:213], v[68:71]
	v_mfma_f32_16x16x32_bf16 v[72:75], v[162:165], v[210:213], v[72:75]
	s_barrier
	s_setprio 3
	v_mfma_f32_16x16x32_bf16 v[72:75], v[166:169], v[214:217], v[72:75]
	v_mfma_f32_16x16x32_bf16 v[76:79], v[158:161], v[214:217], v[76:79]
	v_mfma_f32_16x16x32_bf16 v[76:79], v[154:157], v[210:213], v[76:79]
	s_setprio 0
	s_add_i32 s34, s59, s43
	v_lshl_add_u64 v[186:187], v[218:219], 0, s[14:15]
	s_mov_b32 m0, s34
	s_nop 0
	global_load_lds_dwordx4 v[186:187], off
	s_add_i32 m0, s34, 0x2000
	s_add_u32 s30, s30, 0x100080
	v_lshl_add_u64 v[186:187], v[220:221], 0, s[14:15]
	s_addc_u32 s31, s31, 0
	s_add_i32 s34, s60, s43
	global_load_lds_dwordx4 v[186:187], off
	v_lshl_add_u64 v[186:187], s[30:31], 0, v[130:131]
	s_mov_b32 m0, s34
	s_nop 0
	global_load_lds_dwordx4 v[186:187], off
	v_lshl_add_u64 v[186:187], s[30:31], 0, v[134:135]
	s_add_i32 m0, s34, 0x2000
	s_nop 0
	global_load_lds_dwordx4 v[186:187], off
	v_lshl_add_u64 v[186:187], v[222:223], 0, s[16:17]
	s_mov_b32 m0, s49
	s_nop 0
	global_load_lds_dwordx4 v[186:187], off
	v_lshl_add_u64 v[186:187], v[224:225], 0, s[16:17]
	s_mov_b32 m0, s50
	s_nop 0
	global_load_lds_dwordx4 v[186:187], off
	ds_read_b128 v[186:189], v153 offset:49152
	ds_read_b128 v[190:193], v153 offset:50176
	ds_read_b128 v[194:197], v153 offset:51200
	ds_read_b128 v[198:201], v153 offset:52224
	ds_read_b128 v[202:205], v153 offset:53248
	ds_read_b128 v[206:209], v153 offset:54272
	ds_read_b128 v[210:213], v153 offset:55296
	ds_read_b128 v[214:217], v153 offset:56320
	s_waitcnt vmcnt(8)
	s_waitcnt lgkmcnt(0)
	s_barrier
	v_mfma_f32_16x16x32_bf16 v[60:63], v[154:157], v[186:189], v[60:63]
	v_mfma_f32_16x16x32_bf16 v[60:63], v[158:161], v[190:193], v[60:63]
	v_mfma_f32_16x16x32_bf16 v[56:59], v[166:169], v[190:193], v[56:59]
	v_mfma_f32_16x16x32_bf16 v[56:59], v[162:165], v[186:189], v[56:59]
	v_mfma_f32_16x16x32_bf16 v[52:55], v[170:173], v[186:189], v[52:55]
	v_mfma_f32_16x16x32_bf16 v[52:55], v[174:177], v[190:193], v[52:55]
	v_mfma_f32_16x16x32_bf16 v[48:51], v[182:185], v[190:193], v[48:51]
	v_mfma_f32_16x16x32_bf16 v[48:51], v[178:181], v[186:189], v[48:51]
	v_mfma_f32_16x16x32_bf16 v[32:35], v[178:181], v[194:197], v[32:35]
	v_mfma_f32_16x16x32_bf16 v[32:35], v[182:185], v[198:201], v[32:35]
	v_mfma_f32_16x16x32_bf16 v[36:39], v[174:177], v[198:201], v[36:39]
	v_mfma_f32_16x16x32_bf16 v[36:39], v[170:173], v[194:197], v[36:39]
	v_mfma_f32_16x16x32_bf16 v[40:43], v[162:165], v[194:197], v[40:43]
	v_mfma_f32_16x16x32_bf16 v[40:43], v[166:169], v[198:201], v[40:43]
	v_mfma_f32_16x16x32_bf16 v[44:47], v[158:161], v[198:201], v[44:47]
	v_mfma_f32_16x16x32_bf16 v[44:47], v[154:157], v[194:197], v[44:47]
	v_mfma_f32_16x16x32_bf16 v[28:31], v[154:157], v[202:205], v[28:31]
	v_mfma_f32_16x16x32_bf16 v[28:31], v[158:161], v[206:209], v[28:31]
	v_mfma_f32_16x16x32_bf16 v[24:27], v[166:169], v[206:209], v[24:27]
	v_mfma_f32_16x16x32_bf16 v[24:27], v[162:165], v[202:205], v[24:27]
	v_mfma_f32_16x16x32_bf16 v[20:23], v[170:173], v[202:205], v[20:23]
	v_mfma_f32_16x16x32_bf16 v[20:23], v[174:177], v[206:209], v[20:23]
	v_mfma_f32_16x16x32_bf16 v[16:19], v[182:185], v[206:209], v[16:19]
	v_mfma_f32_16x16x32_bf16 v[16:19], v[178:181], v[202:205], v[16:19]
	v_mfma_f32_16x16x32_bf16 v[0:3], v[178:181], v[210:213], v[0:3]
	v_mfma_f32_16x16x32_bf16 v[0:3], v[182:185], v[214:217], v[0:3]
	v_mfma_f32_16x16x32_bf16 v[4:7], v[174:177], v[214:217], v[4:7]
	v_mfma_f32_16x16x32_bf16 v[4:7], v[170:173], v[210:213], v[4:7]
	v_mfma_f32_16x16x32_bf16 v[8:11], v[162:165], v[210:213], v[8:11]
	s_barrier
	s_setprio 3
	v_mfma_f32_16x16x32_bf16 v[8:11], v[166:169], v[214:217], v[8:11]
	v_mfma_f32_16x16x32_bf16 v[12:15], v[158:161], v[214:217], v[12:15]
	v_mfma_f32_16x16x32_bf16 v[12:15], v[154:157], v[210:213], v[12:15]
	s_setprio 0
	s_add_i32 s58, s58, 2
	s_add_u32 s56, s56, 0x100
	s_addc_u32 s57, s57, 0
	s_add_u32 s28, s28, 0x1000
	s_addc_u32 s29, s29, 0
	v_lshl_add_u64 v[146:147], v[146:147], 0, s[18:19]
	s_cmp_gt_u32 s58, 61
	v_lshl_add_u64 v[144:145], v[144:145], 0, s[18:19]
	s_cbranch_scc0 .LBB0_1340
	s_andn2_b64 vcc, exec, s[4:5]
	s_cbranch_vccnz .LBB0_1332
	v_mov_b32_e32 v0, 0
	s_mov_b32 s7, s20
	s_mov_b32 s6, s22
	s_mov_b64 s[8:9], s[26:27]
	s_mov_b64 s[10:11], s[24:25]
	s_mov_b32 s48, s53
	v_mov_b32_e32 v1, v0
	v_mov_b32_e32 v2, v0
	v_mov_b32_e32 v3, v0
	v_mov_b32_e32 v4, v0
	v_mov_b32_e32 v5, v0
	v_mov_b32_e32 v6, v0
	v_mov_b32_e32 v7, v0
	v_mov_b32_e32 v16, v0
	v_mov_b32_e32 v17, v0
	v_mov_b32_e32 v18, v0
	v_mov_b32_e32 v19, v0
	v_mov_b32_e32 v20, v0
	v_mov_b32_e32 v21, v0
	v_mov_b32_e32 v22, v0
	v_mov_b32_e32 v23, v0
	v_mov_b32_e32 v32, v0
	v_mov_b32_e32 v33, v0
	v_mov_b32_e32 v34, v0
	v_mov_b32_e32 v35, v0
	v_mov_b32_e32 v36, v0
	v_mov_b32_e32 v37, v0
	v_mov_b32_e32 v38, v0
	v_mov_b32_e32 v39, v0
	v_mov_b32_e32 v48, v0
	v_mov_b32_e32 v49, v0
	v_mov_b32_e32 v50, v0
	v_mov_b32_e32 v51, v0
	v_mov_b32_e32 v52, v0
	v_mov_b32_e32 v53, v0
	v_mov_b32_e32 v54, v0
	v_mov_b32_e32 v55, v0
	v_mov_b32_e32 v8, v0
	v_mov_b32_e32 v9, v0
	v_mov_b32_e32 v10, v0
	v_mov_b32_e32 v11, v0
	v_mov_b32_e32 v12, v0
	v_mov_b32_e32 v13, v0
	v_mov_b32_e32 v14, v0
	v_mov_b32_e32 v15, v0
	v_mov_b32_e32 v24, v0
	v_mov_b32_e32 v25, v0
	v_mov_b32_e32 v26, v0
	v_mov_b32_e32 v27, v0
	v_mov_b32_e32 v28, v0
	v_mov_b32_e32 v29, v0
	v_mov_b32_e32 v30, v0
	v_mov_b32_e32 v31, v0
	v_mov_b32_e32 v40, v0
	v_mov_b32_e32 v41, v0
	v_mov_b32_e32 v42, v0
	v_mov_b32_e32 v43, v0
	v_mov_b32_e32 v44, v0
	v_mov_b32_e32 v45, v0
	v_mov_b32_e32 v46, v0
	v_mov_b32_e32 v47, v0
	v_mov_b32_e32 v56, v0
	v_mov_b32_e32 v57, v0
	v_mov_b32_e32 v58, v0
	v_mov_b32_e32 v59, v0
	v_mov_b32_e32 v60, v0
	v_mov_b32_e32 v61, v0
	v_mov_b32_e32 v62, v0
	v_mov_b32_e32 v63, v0
	v_mov_b32_e32 v64, v0
	v_mov_b32_e32 v65, v0
	v_mov_b32_e32 v66, v0
	v_mov_b32_e32 v67, v0
	v_mov_b32_e32 v68, v0
	v_mov_b32_e32 v69, v0
	v_mov_b32_e32 v70, v0
	v_mov_b32_e32 v71, v0
	v_mov_b32_e32 v80, v0
	v_mov_b32_e32 v81, v0
	v_mov_b32_e32 v82, v0
	v_mov_b32_e32 v83, v0
	v_mov_b32_e32 v84, v0
	v_mov_b32_e32 v85, v0
	v_mov_b32_e32 v86, v0
	v_mov_b32_e32 v87, v0
	v_mov_b32_e32 v96, v0
	v_mov_b32_e32 v97, v0
	v_mov_b32_e32 v98, v0
	v_mov_b32_e32 v99, v0
	v_mov_b32_e32 v100, v0
	v_mov_b32_e32 v101, v0
	v_mov_b32_e32 v102, v0
	v_mov_b32_e32 v103, v0
	v_mov_b32_e32 v112, v0
	v_mov_b32_e32 v113, v0
	v_mov_b32_e32 v114, v0
	v_mov_b32_e32 v115, v0
	v_mov_b32_e32 v116, v0
	v_mov_b32_e32 v117, v0
	v_mov_b32_e32 v118, v0
	v_mov_b32_e32 v119, v0
	v_mov_b32_e32 v72, v0
	v_mov_b32_e32 v73, v0
	v_mov_b32_e32 v74, v0
	v_mov_b32_e32 v75, v0
	v_mov_b32_e32 v76, v0
	v_mov_b32_e32 v77, v0
	v_mov_b32_e32 v78, v0
	v_mov_b32_e32 v79, v0
	v_mov_b32_e32 v88, v0
	v_mov_b32_e32 v89, v0
	v_mov_b32_e32 v90, v0
	v_mov_b32_e32 v91, v0
	v_mov_b32_e32 v92, v0
	v_mov_b32_e32 v93, v0
	v_mov_b32_e32 v94, v0
	v_mov_b32_e32 v95, v0
	v_mov_b32_e32 v104, v0
	v_mov_b32_e32 v105, v0
	v_mov_b32_e32 v106, v0
	v_mov_b32_e32 v107, v0
	v_mov_b32_e32 v108, v0
	v_mov_b32_e32 v109, v0
	v_mov_b32_e32 v110, v0
	v_mov_b32_e32 v111, v0
	v_mov_b32_e32 v120, v0
	v_mov_b32_e32 v121, v0
	v_mov_b32_e32 v122, v0
	v_mov_b32_e32 v123, v0
	v_mov_b32_e32 v124, v0
	v_mov_b32_e32 v125, v0
	v_mov_b32_e32 v126, v0
	v_mov_b32_e32 v127, v0
	s_branch .LBB0_1332

.LBB0_1435:
	ds_read_b128 v[128:131], v180
	ds_read_b128 v[132:135], v180 offset:1024
	ds_read_b128 v[136:139], v180 offset:2048
	ds_read_b128 v[140:143], v180 offset:3072
	ds_read_b128 v[144:147], v181
	ds_read_b128 v[148:151], v181 offset:1024
	ds_read_b128 v[170:173], v181 offset:2048
	ds_read_b128 v[174:177], v181 offset:3072
	s_add_u32 s26, s24, 0xfffc0080
	s_addc_u32 s27, s25, -1
	s_cmp_eq_u32 s35, 12
	s_cselect_b32 s29, s1, s27
	s_cselect_b32 s28, s19, s26
	s_cselect_b32 s27, s17, s34
	s_cselect_b32 s26, s30, s31
	v_lshl_add_u64 v[184:185], s[24:25], 0, v[162:163]
	s_add_i32 m0, s40, 0xc000
	s_nop 0
	global_load_lds_dwordx4 v[184:185], off
	v_lshl_add_u64 v[184:185], s[24:25], 0, v[164:165]
	s_add_i32 m0, s40, 0xe000
	s_nop 0
	global_load_lds_dwordx4 v[184:185], off
	ds_read_b128 v[184:187], v182
	ds_read_b128 v[188:191], v182 offset:1024
	ds_read_b128 v[192:195], v182 offset:2048
	ds_read_b128 v[196:199], v182 offset:3072
	ds_read_b128 v[200:203], v182 offset:4096
	ds_read_b128 v[204:207], v182 offset:5120
	ds_read_b128 v[208:211], v182 offset:6144
	ds_read_b128 v[212:215], v182 offset:7168
	s_waitcnt vmcnt(8)
	s_waitcnt lgkmcnt(0)
	s_barrier
	v_mfma_f32_16x16x32_bf16 v[124:127], v[128:131], v[184:187], v[124:127]
	v_mfma_f32_16x16x32_bf16 v[124:127], v[132:135], v[188:191], v[124:127]
	v_mfma_f32_16x16x32_bf16 v[120:123], v[140:143], v[188:191], v[120:123]
	v_mfma_f32_16x16x32_bf16 v[120:123], v[136:139], v[184:187], v[120:123]
	v_mfma_f32_16x16x32_bf16 v[116:119], v[144:147], v[184:187], v[116:119]
	v_mfma_f32_16x16x32_bf16 v[116:119], v[148:151], v[188:191], v[116:119]
	v_mfma_f32_16x16x32_bf16 v[112:115], v[174:177], v[188:191], v[112:115]
	v_mfma_f32_16x16x32_bf16 v[112:115], v[170:173], v[184:187], v[112:115]
	v_mfma_f32_16x16x32_bf16 v[96:99], v[170:173], v[192:195], v[96:99]
	v_mfma_f32_16x16x32_bf16 v[96:99], v[174:177], v[196:199], v[96:99]
	v_mfma_f32_16x16x32_bf16 v[100:103], v[148:151], v[196:199], v[100:103]
	v_mfma_f32_16x16x32_bf16 v[100:103], v[144:147], v[192:195], v[100:103]
	v_mfma_f32_16x16x32_bf16 v[104:107], v[136:139], v[192:195], v[104:107]
	v_mfma_f32_16x16x32_bf16 v[104:107], v[140:143], v[196:199], v[104:107]
	v_mfma_f32_16x16x32_bf16 v[108:111], v[132:135], v[196:199], v[108:111]
	v_mfma_f32_16x16x32_bf16 v[108:111], v[128:131], v[192:195], v[108:111]
	v_mfma_f32_16x16x32_bf16 v[92:95], v[128:131], v[200:203], v[92:95]
	v_mfma_f32_16x16x32_bf16 v[92:95], v[132:135], v[204:207], v[92:95]
	v_mfma_f32_16x16x32_bf16 v[88:91], v[140:143], v[204:207], v[88:91]
	v_mfma_f32_16x16x32_bf16 v[88:91], v[136:139], v[200:203], v[88:91]
	v_mfma_f32_16x16x32_bf16 v[84:87], v[144:147], v[200:203], v[84:87]
	v_mfma_f32_16x16x32_bf16 v[84:87], v[148:151], v[204:207], v[84:87]
	v_mfma_f32_16x16x32_bf16 v[80:83], v[174:177], v[204:207], v[80:83]
	v_mfma_f32_16x16x32_bf16 v[80:83], v[170:173], v[200:203], v[80:83]
	v_mfma_f32_16x16x32_bf16 v[64:67], v[170:173], v[208:211], v[64:67]
	v_mfma_f32_16x16x32_bf16 v[64:67], v[174:177], v[212:215], v[64:67]
	v_mfma_f32_16x16x32_bf16 v[68:71], v[148:151], v[212:215], v[68:71]
	v_mfma_f32_16x16x32_bf16 v[68:71], v[144:147], v[208:211], v[68:71]
	v_mfma_f32_16x16x32_bf16 v[72:75], v[136:139], v[208:211], v[72:75]
	s_barrier
	s_setprio 3
	v_mfma_f32_16x16x32_bf16 v[72:75], v[140:143], v[212:215], v[72:75]
	v_mfma_f32_16x16x32_bf16 v[76:79], v[132:135], v[212:215], v[76:79]
	v_mfma_f32_16x16x32_bf16 v[76:79], v[128:131], v[208:211], v[76:79]
	s_setprio 0
	s_add_i32 s54, s50, s39
	v_lshl_add_u64 v[216:217], s[26:27], 0, v[154:155]
	s_mov_b32 m0, s54
	v_lshl_add_u64 v[218:219], s[26:27], 0, v[158:159]
	global_load_lds_dwordx4 v[216:217], off
	s_add_i32 m0, s54, 0x2000
	s_add_u32 s54, s26, 0x100000
	s_addc_u32 s55, s27, 0
	s_add_i32 s56, s51, s39
	global_load_lds_dwordx4 v[218:219], off
	v_lshl_add_u64 v[184:185], s[54:55], 0, v[154:155]
	s_mov_b32 m0, s56
	v_lshl_add_u64 v[220:221], s[28:29], 0, v[152:153]
	global_load_lds_dwordx4 v[184:185], off
	v_lshl_add_u64 v[184:185], s[54:55], 0, v[158:159]
	s_add_i32 m0, s56, 0x2000
	v_lshl_add_u64 v[222:223], s[28:29], 0, v[156:157]
	global_load_lds_dwordx4 v[184:185], off
	s_mov_b32 m0, s40
	s_nop 0
	global_load_lds_dwordx4 v[220:221], off
	s_mov_b32 m0, s41
	s_nop 0
	global_load_lds_dwordx4 v[222:223], off
	ds_read_b128 v[184:187], v182 offset:16384
	ds_read_b128 v[188:191], v182 offset:17408
	ds_read_b128 v[192:195], v182 offset:18432
	ds_read_b128 v[196:199], v182 offset:19456
	ds_read_b128 v[200:203], v182 offset:20480
	ds_read_b128 v[204:207], v182 offset:21504
	ds_read_b128 v[208:211], v182 offset:22528
	ds_read_b128 v[212:215], v182 offset:23552
	s_waitcnt vmcnt(8)
	s_waitcnt lgkmcnt(0)
	s_barrier
	v_mfma_f32_16x16x32_bf16 v[60:63], v[128:131], v[184:187], v[60:63]
	v_mfma_f32_16x16x32_bf16 v[60:63], v[132:135], v[188:191], v[60:63]
	v_mfma_f32_16x16x32_bf16 v[56:59], v[140:143], v[188:191], v[56:59]
	v_mfma_f32_16x16x32_bf16 v[56:59], v[136:139], v[184:187], v[56:59]
	v_mfma_f32_16x16x32_bf16 v[52:55], v[144:147], v[184:187], v[52:55]
	v_mfma_f32_16x16x32_bf16 v[52:55], v[148:151], v[188:191], v[52:55]
	v_mfma_f32_16x16x32_bf16 v[48:51], v[174:177], v[188:191], v[48:51]
	v_mfma_f32_16x16x32_bf16 v[48:51], v[170:173], v[184:187], v[48:51]
	v_mfma_f32_16x16x32_bf16 v[32:35], v[170:173], v[192:195], v[32:35]
	v_mfma_f32_16x16x32_bf16 v[32:35], v[174:177], v[196:199], v[32:35]
	v_mfma_f32_16x16x32_bf16 v[36:39], v[148:151], v[196:199], v[36:39]
	v_mfma_f32_16x16x32_bf16 v[36:39], v[144:147], v[192:195], v[36:39]
	v_mfma_f32_16x16x32_bf16 v[40:43], v[136:139], v[192:195], v[40:43]
	v_mfma_f32_16x16x32_bf16 v[40:43], v[140:143], v[196:199], v[40:43]
	v_mfma_f32_16x16x32_bf16 v[44:47], v[132:135], v[196:199], v[44:47]
	v_mfma_f32_16x16x32_bf16 v[44:47], v[128:131], v[192:195], v[44:47]
	v_mfma_f32_16x16x32_bf16 v[28:31], v[128:131], v[200:203], v[28:31]
	v_mfma_f32_16x16x32_bf16 v[28:31], v[132:135], v[204:207], v[28:31]
	v_mfma_f32_16x16x32_bf16 v[24:27], v[140:143], v[204:207], v[24:27]
	v_mfma_f32_16x16x32_bf16 v[24:27], v[136:139], v[200:203], v[24:27]
	v_mfma_f32_16x16x32_bf16 v[20:23], v[144:147], v[200:203], v[20:23]
	v_mfma_f32_16x16x32_bf16 v[20:23], v[148:151], v[204:207], v[20:23]
	v_mfma_f32_16x16x32_bf16 v[16:19], v[174:177], v[204:207], v[16:19]
	v_mfma_f32_16x16x32_bf16 v[16:19], v[170:173], v[200:203], v[16:19]
	v_mfma_f32_16x16x32_bf16 v[0:3], v[170:173], v[208:211], v[0:3]
	v_mfma_f32_16x16x32_bf16 v[0:3], v[174:177], v[212:215], v[0:3]
	v_mfma_f32_16x16x32_bf16 v[4:7], v[148:151], v[212:215], v[4:7]
	v_mfma_f32_16x16x32_bf16 v[4:7], v[144:147], v[208:211], v[4:7]
	v_mfma_f32_16x16x32_bf16 v[8:11], v[136:139], v[208:211], v[8:11]
	s_barrier
	s_setprio 3
	v_mfma_f32_16x16x32_bf16 v[8:11], v[140:143], v[212:215], v[8:11]
	v_mfma_f32_16x16x32_bf16 v[12:15], v[132:135], v[212:215], v[12:15]
	v_mfma_f32_16x16x32_bf16 v[12:15], v[128:131], v[208:211], v[12:15]
	s_setprio 0
	s_add_i32 s54, 0, 0x18000
	s_add_i32 s55, 0, 0x1c000
	v_add_u32_e32 v140, s54, v178
	v_add_u32_e32 v174, s55, v178
	ds_read_b128 v[128:131], v140
	ds_read_b128 v[132:135], v140 offset:1024
	ds_read_b128 v[136:139], v140 offset:2048
	ds_read_b128 v[140:143], v140 offset:3072
	ds_read_b128 v[144:147], v174
	ds_read_b128 v[148:151], v174 offset:1024
	ds_read_b128 v[170:173], v174 offset:2048
	ds_read_b128 v[174:177], v174 offset:3072
	s_add_u32 s28, s28, 0x40000
	s_addc_u32 s29, s29, 0
	s_mov_b32 m0, s42
	v_lshl_add_u64 v[184:185], s[28:29], 0, v[152:153]
	global_load_lds_dwordx4 v[184:185], off
	v_lshl_add_u64 v[184:185], s[28:29], 0, v[156:157]
	s_mov_b32 m0, s43
	s_nop 0
	global_load_lds_dwordx4 v[184:185], off
	ds_read_b128 v[184:187], v182 offset:32768
	ds_read_b128 v[188:191], v182 offset:33792
	ds_read_b128 v[192:195], v182 offset:34816
	ds_read_b128 v[196:199], v182 offset:35840
	ds_read_b128 v[200:203], v182 offset:36864
	ds_read_b128 v[204:207], v182 offset:37888
	ds_read_b128 v[208:211], v182 offset:38912
	ds_read_b128 v[212:215], v182 offset:39936
	s_waitcnt vmcnt(8)
	s_waitcnt lgkmcnt(0)
	s_barrier
	v_mfma_f32_16x16x32_bf16 v[124:127], v[128:131], v[184:187], v[124:127]
	v_mfma_f32_16x16x32_bf16 v[124:127], v[132:135], v[188:191], v[124:127]
	v_mfma_f32_16x16x32_bf16 v[120:123], v[140:143], v[188:191], v[120:123]
	v_mfma_f32_16x16x32_bf16 v[120:123], v[136:139], v[184:187], v[120:123]
	v_mfma_f32_16x16x32_bf16 v[116:119], v[144:147], v[184:187], v[116:119]
	v_mfma_f32_16x16x32_bf16 v[116:119], v[148:151], v[188:191], v[116:119]
	v_mfma_f32_16x16x32_bf16 v[112:115], v[174:177], v[188:191], v[112:115]
	v_mfma_f32_16x16x32_bf16 v[112:115], v[170:173], v[184:187], v[112:115]
	v_mfma_f32_16x16x32_bf16 v[96:99], v[170:173], v[192:195], v[96:99]
	v_mfma_f32_16x16x32_bf16 v[96:99], v[174:177], v[196:199], v[96:99]
	v_mfma_f32_16x16x32_bf16 v[100:103], v[148:151], v[196:199], v[100:103]
	v_mfma_f32_16x16x32_bf16 v[100:103], v[144:147], v[192:195], v[100:103]
	v_mfma_f32_16x16x32_bf16 v[104:107], v[136:139], v[192:195], v[104:107]
	v_mfma_f32_16x16x32_bf16 v[104:107], v[140:143], v[196:199], v[104:107]
	v_mfma_f32_16x16x32_bf16 v[108:111], v[132:135], v[196:199], v[108:111]
	v_mfma_f32_16x16x32_bf16 v[108:111], v[128:131], v[192:195], v[108:111]
	v_mfma_f32_16x16x32_bf16 v[92:95], v[128:131], v[200:203], v[92:95]
	v_mfma_f32_16x16x32_bf16 v[92:95], v[132:135], v[204:207], v[92:95]
	v_mfma_f32_16x16x32_bf16 v[88:91], v[140:143], v[204:207], v[88:91]
	v_mfma_f32_16x16x32_bf16 v[88:91], v[136:139], v[200:203], v[88:91]
	v_mfma_f32_16x16x32_bf16 v[84:87], v[144:147], v[200:203], v[84:87]
	v_mfma_f32_16x16x32_bf16 v[84:87], v[148:151], v[204:207], v[84:87]
	v_mfma_f32_16x16x32_bf16 v[80:83], v[174:177], v[204:207], v[80:83]
	v_mfma_f32_16x16x32_bf16 v[80:83], v[170:173], v[200:203], v[80:83]
	v_mfma_f32_16x16x32_bf16 v[64:67], v[170:173], v[208:211], v[64:67]
	v_mfma_f32_16x16x32_bf16 v[64:67], v[174:177], v[212:215], v[64:67]
	v_mfma_f32_16x16x32_bf16 v[68:71], v[148:151], v[212:215], v[68:71]
	v_mfma_f32_16x16x32_bf16 v[68:71], v[144:147], v[208:211], v[68:71]
	v_mfma_f32_16x16x32_bf16 v[72:75], v[136:139], v[208:211], v[72:75]
	s_barrier
	s_setprio 3
	v_mfma_f32_16x16x32_bf16 v[72:75], v[140:143], v[212:215], v[72:75]
	v_mfma_f32_16x16x32_bf16 v[76:79], v[132:135], v[212:215], v[76:79]
	v_mfma_f32_16x16x32_bf16 v[76:79], v[128:131], v[208:211], v[76:79]
	s_setprio 0
	s_add_i32 s28, s54, s39
	v_lshl_add_u64 v[184:185], v[216:217], 0, s[14:15]
	s_mov_b32 m0, s28
	s_nop 0
	global_load_lds_dwordx4 v[184:185], off
	s_add_i32 m0, s28, 0x2000
	s_add_u32 s26, s26, 0x100080
	v_lshl_add_u64 v[184:185], v[218:219], 0, s[14:15]
	s_addc_u32 s27, s27, 0
	s_add_i32 s28, s55, s39
	global_load_lds_dwordx4 v[184:185], off
	v_lshl_add_u64 v[184:185], s[26:27], 0, v[154:155]
	s_mov_b32 m0, s28
	s_nop 0
	global_load_lds_dwordx4 v[184:185], off
	v_lshl_add_u64 v[184:185], s[26:27], 0, v[158:159]
	s_add_i32 m0, s28, 0x2000
	s_nop 0
	global_load_lds_dwordx4 v[184:185], off
	v_lshl_add_u64 v[184:185], v[220:221], 0, s[14:15]
	s_mov_b32 m0, s45
	s_nop 0
	global_load_lds_dwordx4 v[184:185], off
	v_lshl_add_u64 v[184:185], v[222:223], 0, s[14:15]
	s_mov_b32 m0, s46
	s_nop 0
	global_load_lds_dwordx4 v[184:185], off
	ds_read_b128 v[184:187], v182 offset:49152
	ds_read_b128 v[188:191], v182 offset:50176
	ds_read_b128 v[192:195], v182 offset:51200
	ds_read_b128 v[196:199], v182 offset:52224
	ds_read_b128 v[200:203], v182 offset:53248
	ds_read_b128 v[204:207], v182 offset:54272
	ds_read_b128 v[208:211], v182 offset:55296
	ds_read_b128 v[212:215], v182 offset:56320
	s_waitcnt vmcnt(8)
	s_waitcnt lgkmcnt(0)
	s_barrier
	v_mfma_f32_16x16x32_bf16 v[60:63], v[128:131], v[184:187], v[60:63]
	v_mfma_f32_16x16x32_bf16 v[60:63], v[132:135], v[188:191], v[60:63]
	v_mfma_f32_16x16x32_bf16 v[56:59], v[140:143], v[188:191], v[56:59]
	v_mfma_f32_16x16x32_bf16 v[56:59], v[136:139], v[184:187], v[56:59]
	v_mfma_f32_16x16x32_bf16 v[52:55], v[144:147], v[184:187], v[52:55]
	v_mfma_f32_16x16x32_bf16 v[52:55], v[148:151], v[188:191], v[52:55]
	v_mfma_f32_16x16x32_bf16 v[48:51], v[174:177], v[188:191], v[48:51]
	v_mfma_f32_16x16x32_bf16 v[48:51], v[170:173], v[184:187], v[48:51]
	v_mfma_f32_16x16x32_bf16 v[32:35], v[170:173], v[192:195], v[32:35]
	v_mfma_f32_16x16x32_bf16 v[32:35], v[174:177], v[196:199], v[32:35]
	v_mfma_f32_16x16x32_bf16 v[36:39], v[148:151], v[196:199], v[36:39]
	v_mfma_f32_16x16x32_bf16 v[36:39], v[144:147], v[192:195], v[36:39]
	v_mfma_f32_16x16x32_bf16 v[40:43], v[136:139], v[192:195], v[40:43]
	v_mfma_f32_16x16x32_bf16 v[40:43], v[140:143], v[196:199], v[40:43]
	v_mfma_f32_16x16x32_bf16 v[44:47], v[132:135], v[196:199], v[44:47]
	v_mfma_f32_16x16x32_bf16 v[44:47], v[128:131], v[192:195], v[44:47]
	v_mfma_f32_16x16x32_bf16 v[28:31], v[128:131], v[200:203], v[28:31]
	v_mfma_f32_16x16x32_bf16 v[28:31], v[132:135], v[204:207], v[28:31]
	v_mfma_f32_16x16x32_bf16 v[24:27], v[140:143], v[204:207], v[24:27]
	v_mfma_f32_16x16x32_bf16 v[24:27], v[136:139], v[200:203], v[24:27]
	v_mfma_f32_16x16x32_bf16 v[20:23], v[144:147], v[200:203], v[20:23]
	v_mfma_f32_16x16x32_bf16 v[20:23], v[148:151], v[204:207], v[20:23]
	v_mfma_f32_16x16x32_bf16 v[16:19], v[174:177], v[204:207], v[16:19]
	v_mfma_f32_16x16x32_bf16 v[16:19], v[170:173], v[200:203], v[16:19]
	v_mfma_f32_16x16x32_bf16 v[0:3], v[170:173], v[208:211], v[0:3]
	v_mfma_f32_16x16x32_bf16 v[0:3], v[174:177], v[212:215], v[0:3]
	v_mfma_f32_16x16x32_bf16 v[4:7], v[148:151], v[212:215], v[4:7]
	v_mfma_f32_16x16x32_bf16 v[4:7], v[144:147], v[208:211], v[4:7]
	v_mfma_f32_16x16x32_bf16 v[8:11], v[136:139], v[208:211], v[8:11]
	s_barrier
	s_setprio 3
	v_mfma_f32_16x16x32_bf16 v[8:11], v[140:143], v[212:215], v[8:11]
	v_mfma_f32_16x16x32_bf16 v[12:15], v[132:135], v[212:215], v[12:15]
	v_mfma_f32_16x16x32_bf16 v[12:15], v[128:131], v[208:211], v[12:15]
	s_setprio 0
	s_add_i32 s35, s35, 2
	s_add_u32 s24, s24, 0x100
	s_addc_u32 s25, s25, 0
	s_add_u32 s31, s31, 0x100
	s_addc_u32 s34, s34, 0
	s_cmp_gt_u32 s35, 13
	s_cbranch_scc0 .LBB0_1435

.LBB0_1543:
	ds_read_b128 v[128:131], v167
	ds_read_b128 v[154:157], v167 offset:1024
	ds_read_b128 v[172:175], v167 offset:2048
	ds_read_b128 v[176:179], v167 offset:3072
	ds_read_b128 v[180:183], v168
	ds_read_b128 v[184:187], v168 offset:1024
	ds_read_b128 v[188:191], v168 offset:2048
	ds_read_b128 v[192:195], v168 offset:3072
	s_add_u32 s22, s20, 0x1000
	s_addc_u32 s23, s21, 0
	s_cmp_eq_u32 s54, 60
	s_cselect_b32 s27, s13, s23
	s_cselect_b32 s26, s50, s22
	s_cselect_b32 s25, s11, s53
	s_cselect_b32 s24, s51, s52
	v_lshl_add_u64 v[160:161], s[20:21], 0, v[144:145]
	s_add_i32 m0, s19, 0xc000
	s_nop 0
	global_load_lds_dwordx4 v[160:161], off
	v_lshl_add_u64 v[160:161], s[20:21], 0, v[146:147]
	s_add_i32 m0, s19, 0xe000
	s_nop 0
	global_load_lds_dwordx4 v[160:161], off
	ds_read_b128 v[196:199], v169
	ds_read_b128 v[200:203], v169 offset:1024
	ds_read_b128 v[204:207], v169 offset:2048
	ds_read_b128 v[208:211], v169 offset:3072
	ds_read_b128 v[212:215], v169 offset:4096
	ds_read_b128 v[216:219], v169 offset:5120
	ds_read_b128 v[220:223], v169 offset:6144
	ds_read_b128 v[224:227], v169 offset:7168
	s_waitcnt vmcnt(8)
	s_waitcnt lgkmcnt(0)
	s_barrier
	v_mfma_f32_16x16x32_bf16 v[124:127], v[128:131], v[196:199], v[124:127]
	v_mfma_f32_16x16x32_bf16 v[124:127], v[154:157], v[200:203], v[124:127]
	v_mfma_f32_16x16x32_bf16 v[120:123], v[176:179], v[200:203], v[120:123]
	v_mfma_f32_16x16x32_bf16 v[120:123], v[172:175], v[196:199], v[120:123]
	v_mfma_f32_16x16x32_bf16 v[116:119], v[180:183], v[196:199], v[116:119]
	v_mfma_f32_16x16x32_bf16 v[116:119], v[184:187], v[200:203], v[116:119]
	v_mfma_f32_16x16x32_bf16 v[112:115], v[192:195], v[200:203], v[112:115]
	v_mfma_f32_16x16x32_bf16 v[112:115], v[188:191], v[196:199], v[112:115]
	v_mfma_f32_16x16x32_bf16 v[96:99], v[188:191], v[204:207], v[96:99]
	v_mfma_f32_16x16x32_bf16 v[96:99], v[192:195], v[208:211], v[96:99]
	v_mfma_f32_16x16x32_bf16 v[100:103], v[184:187], v[208:211], v[100:103]
	v_mfma_f32_16x16x32_bf16 v[100:103], v[180:183], v[204:207], v[100:103]
	v_mfma_f32_16x16x32_bf16 v[104:107], v[172:175], v[204:207], v[104:107]
	v_mfma_f32_16x16x32_bf16 v[104:107], v[176:179], v[208:211], v[104:107]
	v_mfma_f32_16x16x32_bf16 v[108:111], v[154:157], v[208:211], v[108:111]
	v_mfma_f32_16x16x32_bf16 v[108:111], v[128:131], v[204:207], v[108:111]
	v_mfma_f32_16x16x32_bf16 v[92:95], v[128:131], v[212:215], v[92:95]
	v_mfma_f32_16x16x32_bf16 v[92:95], v[154:157], v[216:219], v[92:95]
	v_mfma_f32_16x16x32_bf16 v[88:91], v[176:179], v[216:219], v[88:91]
	v_mfma_f32_16x16x32_bf16 v[88:91], v[172:175], v[212:215], v[88:91]
	v_mfma_f32_16x16x32_bf16 v[84:87], v[180:183], v[212:215], v[84:87]
	v_mfma_f32_16x16x32_bf16 v[84:87], v[184:187], v[216:219], v[84:87]
	v_mfma_f32_16x16x32_bf16 v[80:83], v[192:195], v[216:219], v[80:83]
	v_mfma_f32_16x16x32_bf16 v[80:83], v[188:191], v[212:215], v[80:83]
	v_mfma_f32_16x16x32_bf16 v[64:67], v[188:191], v[220:223], v[64:67]
	v_mfma_f32_16x16x32_bf16 v[64:67], v[192:195], v[224:227], v[64:67]
	v_mfma_f32_16x16x32_bf16 v[68:71], v[184:187], v[224:227], v[68:71]
	v_mfma_f32_16x16x32_bf16 v[68:71], v[180:183], v[220:223], v[68:71]
	v_mfma_f32_16x16x32_bf16 v[72:75], v[172:175], v[220:223], v[72:75]
	s_barrier
	s_setprio 3
	v_mfma_f32_16x16x32_bf16 v[72:75], v[176:179], v[224:227], v[72:75]
	v_mfma_f32_16x16x32_bf16 v[76:79], v[154:157], v[224:227], v[76:79]
	v_mfma_f32_16x16x32_bf16 v[76:79], v[128:131], v[220:223], v[76:79]
	s_setprio 0
	s_add_i32 s20, s45, s30
	v_lshl_add_u64 v[160:161], s[24:25], 0, v[134:135]
	s_mov_b32 m0, s20
	v_lshl_add_u64 v[164:165], s[24:25], 0, v[138:139]
	global_load_lds_dwordx4 v[160:161], off
	s_add_i32 m0, s20, 0x2000
	s_add_u32 s20, s24, 0x100000
	s_addc_u32 s21, s25, 0
	s_add_i32 s55, s46, s30
	global_load_lds_dwordx4 v[164:165], off
	v_lshl_add_u64 v[196:197], s[20:21], 0, v[134:135]
	s_mov_b32 m0, s55
	v_lshl_add_u64 v[228:229], s[26:27], 0, v[132:133]
	global_load_lds_dwordx4 v[196:197], off
	v_lshl_add_u64 v[196:197], s[20:21], 0, v[138:139]
	s_add_i32 m0, s55, 0x2000
	v_lshl_add_u64 v[230:231], s[26:27], 0, v[136:137]
	global_load_lds_dwordx4 v[196:197], off
	s_mov_b32 m0, s19
	s_nop 0
	global_load_lds_dwordx4 v[228:229], off
	s_mov_b32 m0, s36
	s_nop 0
	global_load_lds_dwordx4 v[230:231], off
	ds_read_b128 v[196:199], v169 offset:16384
	ds_read_b128 v[200:203], v169 offset:17408
	ds_read_b128 v[204:207], v169 offset:18432
	ds_read_b128 v[208:211], v169 offset:19456
	ds_read_b128 v[212:215], v169 offset:20480
	ds_read_b128 v[216:219], v169 offset:21504
	ds_read_b128 v[220:223], v169 offset:22528
	ds_read_b128 v[224:227], v169 offset:23552
	s_waitcnt vmcnt(8)
	s_waitcnt lgkmcnt(0)
	s_barrier
	v_mfma_f32_16x16x32_bf16 v[60:63], v[128:131], v[196:199], v[60:63]
	v_mfma_f32_16x16x32_bf16 v[60:63], v[154:157], v[200:203], v[60:63]
	v_mfma_f32_16x16x32_bf16 v[56:59], v[176:179], v[200:203], v[56:59]
	v_mfma_f32_16x16x32_bf16 v[56:59], v[172:175], v[196:199], v[56:59]
	v_mfma_f32_16x16x32_bf16 v[52:55], v[180:183], v[196:199], v[52:55]
	v_mfma_f32_16x16x32_bf16 v[52:55], v[184:187], v[200:203], v[52:55]
	v_mfma_f32_16x16x32_bf16 v[48:51], v[192:195], v[200:203], v[48:51]
	v_mfma_f32_16x16x32_bf16 v[48:51], v[188:191], v[196:199], v[48:51]
	v_mfma_f32_16x16x32_bf16 v[32:35], v[188:191], v[204:207], v[32:35]
	v_mfma_f32_16x16x32_bf16 v[32:35], v[192:195], v[208:211], v[32:35]
	v_mfma_f32_16x16x32_bf16 v[36:39], v[184:187], v[208:211], v[36:39]
	v_mfma_f32_16x16x32_bf16 v[36:39], v[180:183], v[204:207], v[36:39]
	v_mfma_f32_16x16x32_bf16 v[40:43], v[172:175], v[204:207], v[40:43]
	v_mfma_f32_16x16x32_bf16 v[40:43], v[176:179], v[208:211], v[40:43]
	v_mfma_f32_16x16x32_bf16 v[44:47], v[154:157], v[208:211], v[44:47]
	v_mfma_f32_16x16x32_bf16 v[44:47], v[128:131], v[204:207], v[44:47]
	v_mfma_f32_16x16x32_bf16 v[28:31], v[128:131], v[212:215], v[28:31]
	v_mfma_f32_16x16x32_bf16 v[28:31], v[154:157], v[216:219], v[28:31]
	v_mfma_f32_16x16x32_bf16 v[24:27], v[176:179], v[216:219], v[24:27]
	v_mfma_f32_16x16x32_bf16 v[24:27], v[172:175], v[212:215], v[24:27]
	v_mfma_f32_16x16x32_bf16 v[20:23], v[180:183], v[212:215], v[20:23]
	v_mfma_f32_16x16x32_bf16 v[20:23], v[184:187], v[216:219], v[20:23]
	v_mfma_f32_16x16x32_bf16 v[16:19], v[192:195], v[216:219], v[16:19]
	v_mfma_f32_16x16x32_bf16 v[16:19], v[188:191], v[212:215], v[16:19]
	v_mfma_f32_16x16x32_bf16 v[0:3], v[188:191], v[220:223], v[0:3]
	v_mfma_f32_16x16x32_bf16 v[0:3], v[192:195], v[224:227], v[0:3]
	v_mfma_f32_16x16x32_bf16 v[4:7], v[184:187], v[224:227], v[4:7]
	v_mfma_f32_16x16x32_bf16 v[4:7], v[180:183], v[220:223], v[4:7]
	v_mfma_f32_16x16x32_bf16 v[8:11], v[172:175], v[220:223], v[8:11]
	s_barrier
	s_setprio 3
	v_mfma_f32_16x16x32_bf16 v[8:11], v[176:179], v[224:227], v[8:11]
	v_mfma_f32_16x16x32_bf16 v[12:15], v[154:157], v[224:227], v[12:15]
	v_mfma_f32_16x16x32_bf16 v[12:15], v[128:131], v[220:223], v[12:15]
	s_setprio 0
	s_add_i32 s55, 0, 0x18000
	v_add_u32_e32 v153, s55, v159
	s_add_i32 s56, 0, 0x1c000
	ds_read_b128 v[128:131], v153
	ds_read_b128 v[154:157], v153 offset:1024
	ds_read_b128 v[172:175], v153 offset:2048
	ds_read_b128 v[176:179], v153 offset:3072
	v_add_u32_e32 v153, s56, v159
	ds_read_b128 v[180:183], v153
	ds_read_b128 v[184:187], v153 offset:1024
	ds_read_b128 v[188:191], v153 offset:2048
	ds_read_b128 v[192:195], v153 offset:3072
	s_add_u32 s20, s26, 0x100000
	s_addc_u32 s21, s27, 0
	s_mov_b32 m0, s37
	v_lshl_add_u64 v[196:197], s[20:21], 0, v[132:133]
	global_load_lds_dwordx4 v[196:197], off
	v_lshl_add_u64 v[196:197], s[20:21], 0, v[136:137]
	s_mov_b32 m0, s38
	s_nop 0
	global_load_lds_dwordx4 v[196:197], off
	ds_read_b128 v[196:199], v169 offset:32768
	ds_read_b128 v[200:203], v169 offset:33792
	ds_read_b128 v[204:207], v169 offset:34816
	ds_read_b128 v[208:211], v169 offset:35840
	ds_read_b128 v[212:215], v169 offset:36864
	ds_read_b128 v[216:219], v169 offset:37888
	ds_read_b128 v[220:223], v169 offset:38912
	ds_read_b128 v[224:227], v169 offset:39936
	s_waitcnt vmcnt(8)
	s_waitcnt lgkmcnt(0)
	s_barrier
	v_mfma_f32_16x16x32_bf16 v[124:127], v[128:131], v[196:199], v[124:127]
	v_mfma_f32_16x16x32_bf16 v[124:127], v[154:157], v[200:203], v[124:127]
	v_mfma_f32_16x16x32_bf16 v[120:123], v[176:179], v[200:203], v[120:123]
	v_mfma_f32_16x16x32_bf16 v[120:123], v[172:175], v[196:199], v[120:123]
	v_mfma_f32_16x16x32_bf16 v[116:119], v[180:183], v[196:199], v[116:119]
	v_mfma_f32_16x16x32_bf16 v[116:119], v[184:187], v[200:203], v[116:119]
	v_mfma_f32_16x16x32_bf16 v[112:115], v[192:195], v[200:203], v[112:115]
	v_mfma_f32_16x16x32_bf16 v[112:115], v[188:191], v[196:199], v[112:115]
	v_mfma_f32_16x16x32_bf16 v[96:99], v[188:191], v[204:207], v[96:99]
	v_mfma_f32_16x16x32_bf16 v[96:99], v[192:195], v[208:211], v[96:99]
	v_mfma_f32_16x16x32_bf16 v[100:103], v[184:187], v[208:211], v[100:103]
	v_mfma_f32_16x16x32_bf16 v[100:103], v[180:183], v[204:207], v[100:103]
	v_mfma_f32_16x16x32_bf16 v[104:107], v[172:175], v[204:207], v[104:107]
	v_mfma_f32_16x16x32_bf16 v[104:107], v[176:179], v[208:211], v[104:107]
	v_mfma_f32_16x16x32_bf16 v[108:111], v[154:157], v[208:211], v[108:111]
	v_mfma_f32_16x16x32_bf16 v[108:111], v[128:131], v[204:207], v[108:111]
	v_mfma_f32_16x16x32_bf16 v[92:95], v[128:131], v[212:215], v[92:95]
	v_mfma_f32_16x16x32_bf16 v[92:95], v[154:157], v[216:219], v[92:95]
	v_mfma_f32_16x16x32_bf16 v[88:91], v[176:179], v[216:219], v[88:91]
	v_mfma_f32_16x16x32_bf16 v[88:91], v[172:175], v[212:215], v[88:91]
	v_mfma_f32_16x16x32_bf16 v[84:87], v[180:183], v[212:215], v[84:87]
	v_mfma_f32_16x16x32_bf16 v[84:87], v[184:187], v[216:219], v[84:87]
	v_mfma_f32_16x16x32_bf16 v[80:83], v[192:195], v[216:219], v[80:83]
	v_mfma_f32_16x16x32_bf16 v[80:83], v[188:191], v[212:215], v[80:83]
	v_mfma_f32_16x16x32_bf16 v[64:67], v[188:191], v[220:223], v[64:67]
	v_mfma_f32_16x16x32_bf16 v[64:67], v[192:195], v[224:227], v[64:67]
	v_mfma_f32_16x16x32_bf16 v[68:71], v[184:187], v[224:227], v[68:71]
	v_mfma_f32_16x16x32_bf16 v[68:71], v[180:183], v[220:223], v[68:71]
	v_mfma_f32_16x16x32_bf16 v[72:75], v[172:175], v[220:223], v[72:75]
	s_barrier
	s_setprio 3
	v_mfma_f32_16x16x32_bf16 v[72:75], v[176:179], v[224:227], v[72:75]
	v_mfma_f32_16x16x32_bf16 v[76:79], v[154:157], v[224:227], v[76:79]
	v_mfma_f32_16x16x32_bf16 v[76:79], v[128:131], v[220:223], v[76:79]
	s_setprio 0
	s_add_i32 s20, s55, s30
	v_lshl_add_u64 v[160:161], v[160:161], 0, s[8:9]
	s_mov_b32 m0, s20
	s_nop 0
	global_load_lds_dwordx4 v[160:161], off
	s_add_i32 m0, s20, 0x2000
	s_add_u32 s20, s24, 0x100800
	v_lshl_add_u64 v[160:161], v[164:165], 0, s[8:9]
	s_addc_u32 s21, s25, 0
	s_add_i32 s24, s56, s30
	global_load_lds_dwordx4 v[160:161], off
	v_lshl_add_u64 v[160:161], s[20:21], 0, v[134:135]
	s_mov_b32 m0, s24
	s_nop 0
	global_load_lds_dwordx4 v[160:161], off
	v_lshl_add_u64 v[160:161], s[20:21], 0, v[138:139]
	s_add_i32 m0, s24, 0x2000
	s_nop 0
	global_load_lds_dwordx4 v[160:161], off
	v_lshl_add_u64 v[160:161], v[228:229], 0, s[8:9]
	s_mov_b32 m0, s41
	s_nop 0
	global_load_lds_dwordx4 v[160:161], off
	v_lshl_add_u64 v[160:161], v[230:231], 0, s[8:9]
	s_mov_b32 m0, s42
	s_nop 0
	global_load_lds_dwordx4 v[160:161], off
	ds_read_b128 v[196:199], v169 offset:49152
	ds_read_b128 v[200:203], v169 offset:50176
	ds_read_b128 v[204:207], v169 offset:51200
	ds_read_b128 v[208:211], v169 offset:52224
	ds_read_b128 v[212:215], v169 offset:53248
	ds_read_b128 v[216:219], v169 offset:54272
	ds_read_b128 v[220:223], v169 offset:55296
	ds_read_b128 v[224:227], v169 offset:56320
	s_waitcnt vmcnt(8)
	s_waitcnt lgkmcnt(0)
	s_barrier
	v_mfma_f32_16x16x32_bf16 v[60:63], v[128:131], v[196:199], v[60:63]
	v_mfma_f32_16x16x32_bf16 v[60:63], v[154:157], v[200:203], v[60:63]
	v_mfma_f32_16x16x32_bf16 v[56:59], v[176:179], v[200:203], v[56:59]
	v_mfma_f32_16x16x32_bf16 v[56:59], v[172:175], v[196:199], v[56:59]
	v_mfma_f32_16x16x32_bf16 v[52:55], v[180:183], v[196:199], v[52:55]
	v_mfma_f32_16x16x32_bf16 v[52:55], v[184:187], v[200:203], v[52:55]
	v_mfma_f32_16x16x32_bf16 v[48:51], v[192:195], v[200:203], v[48:51]
	v_mfma_f32_16x16x32_bf16 v[48:51], v[188:191], v[196:199], v[48:51]
	v_mfma_f32_16x16x32_bf16 v[32:35], v[188:191], v[204:207], v[32:35]
	v_mfma_f32_16x16x32_bf16 v[32:35], v[192:195], v[208:211], v[32:35]
	v_mfma_f32_16x16x32_bf16 v[36:39], v[184:187], v[208:211], v[36:39]
	v_mfma_f32_16x16x32_bf16 v[36:39], v[180:183], v[204:207], v[36:39]
	v_mfma_f32_16x16x32_bf16 v[40:43], v[172:175], v[204:207], v[40:43]
	v_mfma_f32_16x16x32_bf16 v[40:43], v[176:179], v[208:211], v[40:43]
	v_mfma_f32_16x16x32_bf16 v[44:47], v[154:157], v[208:211], v[44:47]
	v_mfma_f32_16x16x32_bf16 v[44:47], v[128:131], v[204:207], v[44:47]
	v_mfma_f32_16x16x32_bf16 v[28:31], v[128:131], v[212:215], v[28:31]
	v_mfma_f32_16x16x32_bf16 v[28:31], v[154:157], v[216:219], v[28:31]
	v_mfma_f32_16x16x32_bf16 v[24:27], v[176:179], v[216:219], v[24:27]
	v_mfma_f32_16x16x32_bf16 v[24:27], v[172:175], v[212:215], v[24:27]
	v_mfma_f32_16x16x32_bf16 v[20:23], v[180:183], v[212:215], v[20:23]
	v_mfma_f32_16x16x32_bf16 v[20:23], v[184:187], v[216:219], v[20:23]
	v_mfma_f32_16x16x32_bf16 v[16:19], v[192:195], v[216:219], v[16:19]
	v_mfma_f32_16x16x32_bf16 v[16:19], v[188:191], v[212:215], v[16:19]
	v_mfma_f32_16x16x32_bf16 v[0:3], v[188:191], v[220:223], v[0:3]
	v_mfma_f32_16x16x32_bf16 v[0:3], v[192:195], v[224:227], v[0:3]
	v_mfma_f32_16x16x32_bf16 v[4:7], v[184:187], v[224:227], v[4:7]
	v_mfma_f32_16x16x32_bf16 v[4:7], v[180:183], v[220:223], v[4:7]
	v_mfma_f32_16x16x32_bf16 v[8:11], v[172:175], v[220:223], v[8:11]
	s_barrier
	s_setprio 3
	v_mfma_f32_16x16x32_bf16 v[8:11], v[176:179], v[224:227], v[8:11]
	v_mfma_f32_16x16x32_bf16 v[12:15], v[154:157], v[224:227], v[12:15]
	v_mfma_f32_16x16x32_bf16 v[12:15], v[128:131], v[220:223], v[12:15]
	s_setprio 0
	s_add_i32 s54, s54, 2
	s_add_u32 s52, s52, 0x1000
	s_addc_u32 s53, s53, 0
	s_cmp_gt_u32 s54, 61
	s_mov_b64 s[20:21], s[22:23]
	s_cbranch_scc0 .LBB0_1543

.LBB0_1625:
	ds_read_b128 v[128:131], v177
	ds_read_b128 v[132:135], v177 offset:1024
	ds_read_b128 v[136:139], v177 offset:2048
	ds_read_b128 v[140:143], v177 offset:3072
	ds_read_b128 v[144:147], v178
	ds_read_b128 v[148:151], v178 offset:1024
	ds_read_b128 v[170:173], v178 offset:2048
	ds_read_b128 v[182:185], v178 offset:3072
	s_add_u32 s24, s22, 0xffc00800
	s_addc_u32 s25, s23, -1
	s_cmpk_eq_i32 s57, 0xfc
	s_cselect_b32 s27, s29, s25
	s_cselect_b32 s26, s53, s24
	s_cselect_b32 s25, s17, s56
	s_cselect_b32 s24, s54, s55
	v_lshl_add_u64 v[186:187], s[22:23], 0, v[162:163]
	s_add_i32 m0, s38, 0xc000
	s_nop 0
	global_load_lds_dwordx4 v[186:187], off
	v_lshl_add_u64 v[186:187], s[22:23], 0, v[164:165]
	s_add_i32 m0, s38, 0xe000
	s_nop 0
	global_load_lds_dwordx4 v[186:187], off
	ds_read_b128 v[186:189], v179
	ds_read_b128 v[190:193], v179 offset:1024
	ds_read_b128 v[194:197], v179 offset:2048
	ds_read_b128 v[198:201], v179 offset:3072
	ds_read_b128 v[202:205], v179 offset:4096
	ds_read_b128 v[206:209], v179 offset:5120
	ds_read_b128 v[210:213], v179 offset:6144
	ds_read_b128 v[214:217], v179 offset:7168
	s_waitcnt vmcnt(8)
	s_waitcnt lgkmcnt(0)
	s_barrier
	v_mfma_f32_16x16x32_bf16 v[124:127], v[128:131], v[186:189], v[124:127]
	v_mfma_f32_16x16x32_bf16 v[124:127], v[132:135], v[190:193], v[124:127]
	v_mfma_f32_16x16x32_bf16 v[120:123], v[140:143], v[190:193], v[120:123]
	v_mfma_f32_16x16x32_bf16 v[120:123], v[136:139], v[186:189], v[120:123]
	v_mfma_f32_16x16x32_bf16 v[116:119], v[144:147], v[186:189], v[116:119]
	v_mfma_f32_16x16x32_bf16 v[116:119], v[148:151], v[190:193], v[116:119]
	v_mfma_f32_16x16x32_bf16 v[112:115], v[182:185], v[190:193], v[112:115]
	v_mfma_f32_16x16x32_bf16 v[112:115], v[170:173], v[186:189], v[112:115]
	v_mfma_f32_16x16x32_bf16 v[96:99], v[170:173], v[194:197], v[96:99]
	v_mfma_f32_16x16x32_bf16 v[96:99], v[182:185], v[198:201], v[96:99]
	v_mfma_f32_16x16x32_bf16 v[100:103], v[148:151], v[198:201], v[100:103]
	v_mfma_f32_16x16x32_bf16 v[100:103], v[144:147], v[194:197], v[100:103]
	v_mfma_f32_16x16x32_bf16 v[104:107], v[136:139], v[194:197], v[104:107]
	v_mfma_f32_16x16x32_bf16 v[104:107], v[140:143], v[198:201], v[104:107]
	v_mfma_f32_16x16x32_bf16 v[108:111], v[132:135], v[198:201], v[108:111]
	v_mfma_f32_16x16x32_bf16 v[108:111], v[128:131], v[194:197], v[108:111]
	v_mfma_f32_16x16x32_bf16 v[92:95], v[128:131], v[202:205], v[92:95]
	v_mfma_f32_16x16x32_bf16 v[92:95], v[132:135], v[206:209], v[92:95]
	v_mfma_f32_16x16x32_bf16 v[88:91], v[140:143], v[206:209], v[88:91]
	v_mfma_f32_16x16x32_bf16 v[88:91], v[136:139], v[202:205], v[88:91]
	v_mfma_f32_16x16x32_bf16 v[84:87], v[144:147], v[202:205], v[84:87]
	v_mfma_f32_16x16x32_bf16 v[84:87], v[148:151], v[206:209], v[84:87]
	v_mfma_f32_16x16x32_bf16 v[80:83], v[182:185], v[206:209], v[80:83]
	v_mfma_f32_16x16x32_bf16 v[80:83], v[170:173], v[202:205], v[80:83]
	v_mfma_f32_16x16x32_bf16 v[64:67], v[170:173], v[210:213], v[64:67]
	v_mfma_f32_16x16x32_bf16 v[64:67], v[182:185], v[214:217], v[64:67]
	v_mfma_f32_16x16x32_bf16 v[68:71], v[148:151], v[214:217], v[68:71]
	v_mfma_f32_16x16x32_bf16 v[68:71], v[144:147], v[210:213], v[68:71]
	v_mfma_f32_16x16x32_bf16 v[72:75], v[136:139], v[210:213], v[72:75]
	s_barrier
	s_setprio 3
	v_mfma_f32_16x16x32_bf16 v[72:75], v[140:143], v[214:217], v[72:75]
	v_mfma_f32_16x16x32_bf16 v[76:79], v[132:135], v[214:217], v[76:79]
	v_mfma_f32_16x16x32_bf16 v[76:79], v[128:131], v[210:213], v[76:79]
	s_setprio 0
	s_add_i32 s58, s48, s37
	v_lshl_add_u64 v[218:219], s[24:25], 0, v[154:155]
	s_mov_b32 m0, s58
	v_lshl_add_u64 v[220:221], s[24:25], 0, v[158:159]
	global_load_lds_dwordx4 v[218:219], off
	s_add_i32 m0, s58, 0x2000
	s_add_u32 s58, s24, 0x400000
	s_addc_u32 s59, s25, 0
	s_add_i32 s60, s49, s37
	global_load_lds_dwordx4 v[220:221], off
	v_lshl_add_u64 v[186:187], s[58:59], 0, v[154:155]
	s_mov_b32 m0, s60
	v_lshl_add_u64 v[222:223], s[26:27], 0, v[152:153]
	global_load_lds_dwordx4 v[186:187], off
	v_lshl_add_u64 v[186:187], s[58:59], 0, v[158:159]
	s_add_i32 m0, s60, 0x2000
	v_lshl_add_u64 v[224:225], s[26:27], 0, v[156:157]
	global_load_lds_dwordx4 v[186:187], off
	s_mov_b32 m0, s38
	s_nop 0
	global_load_lds_dwordx4 v[222:223], off
	s_mov_b32 m0, s39
	s_nop 0
	global_load_lds_dwordx4 v[224:225], off
	ds_read_b128 v[186:189], v179 offset:16384
	ds_read_b128 v[190:193], v179 offset:17408
	ds_read_b128 v[194:197], v179 offset:18432
	ds_read_b128 v[198:201], v179 offset:19456
	ds_read_b128 v[202:205], v179 offset:20480
	ds_read_b128 v[206:209], v179 offset:21504
	ds_read_b128 v[210:213], v179 offset:22528
	ds_read_b128 v[214:217], v179 offset:23552
	s_waitcnt vmcnt(8)
	s_waitcnt lgkmcnt(0)
	s_barrier
	v_mfma_f32_16x16x32_bf16 v[60:63], v[128:131], v[186:189], v[60:63]
	v_mfma_f32_16x16x32_bf16 v[60:63], v[132:135], v[190:193], v[60:63]
	v_mfma_f32_16x16x32_bf16 v[56:59], v[140:143], v[190:193], v[56:59]
	v_mfma_f32_16x16x32_bf16 v[56:59], v[136:139], v[186:189], v[56:59]
	v_mfma_f32_16x16x32_bf16 v[52:55], v[144:147], v[186:189], v[52:55]
	v_mfma_f32_16x16x32_bf16 v[52:55], v[148:151], v[190:193], v[52:55]
	v_mfma_f32_16x16x32_bf16 v[48:51], v[182:185], v[190:193], v[48:51]
	v_mfma_f32_16x16x32_bf16 v[48:51], v[170:173], v[186:189], v[48:51]
	v_mfma_f32_16x16x32_bf16 v[32:35], v[170:173], v[194:197], v[32:35]
	v_mfma_f32_16x16x32_bf16 v[32:35], v[182:185], v[198:201], v[32:35]
	v_mfma_f32_16x16x32_bf16 v[36:39], v[148:151], v[198:201], v[36:39]
	v_mfma_f32_16x16x32_bf16 v[36:39], v[144:147], v[194:197], v[36:39]
	v_mfma_f32_16x16x32_bf16 v[40:43], v[136:139], v[194:197], v[40:43]
	v_mfma_f32_16x16x32_bf16 v[40:43], v[140:143], v[198:201], v[40:43]
	v_mfma_f32_16x16x32_bf16 v[44:47], v[132:135], v[198:201], v[44:47]
	v_mfma_f32_16x16x32_bf16 v[44:47], v[128:131], v[194:197], v[44:47]
	v_mfma_f32_16x16x32_bf16 v[28:31], v[128:131], v[202:205], v[28:31]
	v_mfma_f32_16x16x32_bf16 v[28:31], v[132:135], v[206:209], v[28:31]
	v_mfma_f32_16x16x32_bf16 v[24:27], v[140:143], v[206:209], v[24:27]
	v_mfma_f32_16x16x32_bf16 v[24:27], v[136:139], v[202:205], v[24:27]
	v_mfma_f32_16x16x32_bf16 v[20:23], v[144:147], v[202:205], v[20:23]
	v_mfma_f32_16x16x32_bf16 v[20:23], v[148:151], v[206:209], v[20:23]
	v_mfma_f32_16x16x32_bf16 v[16:19], v[182:185], v[206:209], v[16:19]
	v_mfma_f32_16x16x32_bf16 v[16:19], v[170:173], v[202:205], v[16:19]
	v_mfma_f32_16x16x32_bf16 v[0:3], v[170:173], v[210:213], v[0:3]
	v_mfma_f32_16x16x32_bf16 v[0:3], v[182:185], v[214:217], v[0:3]
	v_mfma_f32_16x16x32_bf16 v[4:7], v[148:151], v[214:217], v[4:7]
	v_mfma_f32_16x16x32_bf16 v[4:7], v[144:147], v[210:213], v[4:7]
	v_mfma_f32_16x16x32_bf16 v[8:11], v[136:139], v[210:213], v[8:11]
	s_barrier
	s_setprio 3
	v_mfma_f32_16x16x32_bf16 v[8:11], v[140:143], v[214:217], v[8:11]
	v_mfma_f32_16x16x32_bf16 v[12:15], v[132:135], v[214:217], v[12:15]
	v_mfma_f32_16x16x32_bf16 v[12:15], v[128:131], v[210:213], v[12:15]
	s_setprio 0
	s_add_i32 s58, 0, 0x18000
	s_add_i32 s59, 0, 0x1c000
	v_add_u32_e32 v140, s58, v174
	v_add_u32_e32 v181, s59, v174
	ds_read_b128 v[128:131], v140
	ds_read_b128 v[132:135], v140 offset:1024
	ds_read_b128 v[136:139], v140 offset:2048
	ds_read_b128 v[140:143], v140 offset:3072
	ds_read_b128 v[144:147], v181
	ds_read_b128 v[148:151], v181 offset:1024
	ds_read_b128 v[170:173], v181 offset:2048
	ds_read_b128 v[182:185], v181 offset:3072
	s_add_u32 s26, s26, 0x400000
	s_addc_u32 s27, s27, 0
	s_mov_b32 m0, s40
	v_lshl_add_u64 v[186:187], s[26:27], 0, v[152:153]
	global_load_lds_dwordx4 v[186:187], off
	v_lshl_add_u64 v[186:187], s[26:27], 0, v[156:157]
	s_mov_b32 m0, s41
	s_nop 0
	global_load_lds_dwordx4 v[186:187], off
	ds_read_b128 v[186:189], v179 offset:32768
	ds_read_b128 v[190:193], v179 offset:33792
	ds_read_b128 v[194:197], v179 offset:34816
	ds_read_b128 v[198:201], v179 offset:35840
	ds_read_b128 v[202:205], v179 offset:36864
	ds_read_b128 v[206:209], v179 offset:37888
	ds_read_b128 v[210:213], v179 offset:38912
	ds_read_b128 v[214:217], v179 offset:39936
	s_waitcnt vmcnt(8)
	s_waitcnt lgkmcnt(0)
	s_barrier
	v_mfma_f32_16x16x32_bf16 v[124:127], v[128:131], v[186:189], v[124:127]
	v_mfma_f32_16x16x32_bf16 v[124:127], v[132:135], v[190:193], v[124:127]
	v_mfma_f32_16x16x32_bf16 v[120:123], v[140:143], v[190:193], v[120:123]
	v_mfma_f32_16x16x32_bf16 v[120:123], v[136:139], v[186:189], v[120:123]
	v_mfma_f32_16x16x32_bf16 v[116:119], v[144:147], v[186:189], v[116:119]
	v_mfma_f32_16x16x32_bf16 v[116:119], v[148:151], v[190:193], v[116:119]
	v_mfma_f32_16x16x32_bf16 v[112:115], v[182:185], v[190:193], v[112:115]
	v_mfma_f32_16x16x32_bf16 v[112:115], v[170:173], v[186:189], v[112:115]
	v_mfma_f32_16x16x32_bf16 v[96:99], v[170:173], v[194:197], v[96:99]
	v_mfma_f32_16x16x32_bf16 v[96:99], v[182:185], v[198:201], v[96:99]
	v_mfma_f32_16x16x32_bf16 v[100:103], v[148:151], v[198:201], v[100:103]
	v_mfma_f32_16x16x32_bf16 v[100:103], v[144:147], v[194:197], v[100:103]
	v_mfma_f32_16x16x32_bf16 v[104:107], v[136:139], v[194:197], v[104:107]
	v_mfma_f32_16x16x32_bf16 v[104:107], v[140:143], v[198:201], v[104:107]
	v_mfma_f32_16x16x32_bf16 v[108:111], v[132:135], v[198:201], v[108:111]
	v_mfma_f32_16x16x32_bf16 v[108:111], v[128:131], v[194:197], v[108:111]
	v_mfma_f32_16x16x32_bf16 v[92:95], v[128:131], v[202:205], v[92:95]
	v_mfma_f32_16x16x32_bf16 v[92:95], v[132:135], v[206:209], v[92:95]
	v_mfma_f32_16x16x32_bf16 v[88:91], v[140:143], v[206:209], v[88:91]
	v_mfma_f32_16x16x32_bf16 v[88:91], v[136:139], v[202:205], v[88:91]
	v_mfma_f32_16x16x32_bf16 v[84:87], v[144:147], v[202:205], v[84:87]
	v_mfma_f32_16x16x32_bf16 v[84:87], v[148:151], v[206:209], v[84:87]
	v_mfma_f32_16x16x32_bf16 v[80:83], v[182:185], v[206:209], v[80:83]
	v_mfma_f32_16x16x32_bf16 v[80:83], v[170:173], v[202:205], v[80:83]
	v_mfma_f32_16x16x32_bf16 v[64:67], v[170:173], v[210:213], v[64:67]
	v_mfma_f32_16x16x32_bf16 v[64:67], v[182:185], v[214:217], v[64:67]
	v_mfma_f32_16x16x32_bf16 v[68:71], v[148:151], v[214:217], v[68:71]
	v_mfma_f32_16x16x32_bf16 v[68:71], v[144:147], v[210:213], v[68:71]
	v_mfma_f32_16x16x32_bf16 v[72:75], v[136:139], v[210:213], v[72:75]
	s_barrier
	s_setprio 3
	v_mfma_f32_16x16x32_bf16 v[72:75], v[140:143], v[214:217], v[72:75]
	v_mfma_f32_16x16x32_bf16 v[76:79], v[132:135], v[214:217], v[76:79]
	v_mfma_f32_16x16x32_bf16 v[76:79], v[128:131], v[210:213], v[76:79]
	s_setprio 0
	s_add_i32 s26, s58, s37
	v_lshl_add_u64 v[186:187], v[218:219], 0, s[14:15]
	s_mov_b32 m0, s26
	s_nop 0
	global_load_lds_dwordx4 v[186:187], off
	s_add_i32 m0, s26, 0x2000
	s_add_u32 s24, s24, 0x400800
	v_lshl_add_u64 v[186:187], v[220:221], 0, s[14:15]
	s_addc_u32 s25, s25, 0
	s_add_i32 s26, s59, s37
	global_load_lds_dwordx4 v[186:187], off
	v_lshl_add_u64 v[186:187], s[24:25], 0, v[154:155]
	s_mov_b32 m0, s26
	s_nop 0
	global_load_lds_dwordx4 v[186:187], off
	v_lshl_add_u64 v[186:187], s[24:25], 0, v[158:159]
	s_add_i32 m0, s26, 0x2000
	s_nop 0
	global_load_lds_dwordx4 v[186:187], off
	v_lshl_add_u64 v[186:187], v[222:223], 0, s[14:15]
	s_mov_b32 m0, s43
	s_nop 0
	global_load_lds_dwordx4 v[186:187], off
	v_lshl_add_u64 v[186:187], v[224:225], 0, s[14:15]
	s_mov_b32 m0, s44
	s_nop 0
	global_load_lds_dwordx4 v[186:187], off
	ds_read_b128 v[186:189], v179 offset:49152
	ds_read_b128 v[190:193], v179 offset:50176
	ds_read_b128 v[194:197], v179 offset:51200
	ds_read_b128 v[198:201], v179 offset:52224
	ds_read_b128 v[202:205], v179 offset:53248
	ds_read_b128 v[206:209], v179 offset:54272
	ds_read_b128 v[210:213], v179 offset:55296
	ds_read_b128 v[214:217], v179 offset:56320
	s_waitcnt vmcnt(8)
	s_waitcnt lgkmcnt(0)
	s_barrier
	v_mfma_f32_16x16x32_bf16 v[60:63], v[128:131], v[186:189], v[60:63]
	v_mfma_f32_16x16x32_bf16 v[60:63], v[132:135], v[190:193], v[60:63]
	v_mfma_f32_16x16x32_bf16 v[56:59], v[140:143], v[190:193], v[56:59]
	v_mfma_f32_16x16x32_bf16 v[56:59], v[136:139], v[186:189], v[56:59]
	v_mfma_f32_16x16x32_bf16 v[52:55], v[144:147], v[186:189], v[52:55]
	v_mfma_f32_16x16x32_bf16 v[52:55], v[148:151], v[190:193], v[52:55]
	v_mfma_f32_16x16x32_bf16 v[48:51], v[182:185], v[190:193], v[48:51]
	v_mfma_f32_16x16x32_bf16 v[48:51], v[170:173], v[186:189], v[48:51]
	v_mfma_f32_16x16x32_bf16 v[32:35], v[170:173], v[194:197], v[32:35]
	v_mfma_f32_16x16x32_bf16 v[32:35], v[182:185], v[198:201], v[32:35]
	v_mfma_f32_16x16x32_bf16 v[36:39], v[148:151], v[198:201], v[36:39]
	v_mfma_f32_16x16x32_bf16 v[36:39], v[144:147], v[194:197], v[36:39]
	v_mfma_f32_16x16x32_bf16 v[40:43], v[136:139], v[194:197], v[40:43]
	v_mfma_f32_16x16x32_bf16 v[40:43], v[140:143], v[198:201], v[40:43]
	v_mfma_f32_16x16x32_bf16 v[44:47], v[132:135], v[198:201], v[44:47]
	v_mfma_f32_16x16x32_bf16 v[44:47], v[128:131], v[194:197], v[44:47]
	v_mfma_f32_16x16x32_bf16 v[28:31], v[128:131], v[202:205], v[28:31]
	v_mfma_f32_16x16x32_bf16 v[28:31], v[132:135], v[206:209], v[28:31]
	v_mfma_f32_16x16x32_bf16 v[24:27], v[140:143], v[206:209], v[24:27]
	v_mfma_f32_16x16x32_bf16 v[24:27], v[136:139], v[202:205], v[24:27]
	v_mfma_f32_16x16x32_bf16 v[20:23], v[144:147], v[202:205], v[20:23]
	v_mfma_f32_16x16x32_bf16 v[20:23], v[148:151], v[206:209], v[20:23]
	v_mfma_f32_16x16x32_bf16 v[16:19], v[182:185], v[206:209], v[16:19]
	v_mfma_f32_16x16x32_bf16 v[16:19], v[170:173], v[202:205], v[16:19]
	v_mfma_f32_16x16x32_bf16 v[0:3], v[170:173], v[210:213], v[0:3]
	v_mfma_f32_16x16x32_bf16 v[0:3], v[182:185], v[214:217], v[0:3]
	v_mfma_f32_16x16x32_bf16 v[4:7], v[148:151], v[214:217], v[4:7]
	v_mfma_f32_16x16x32_bf16 v[4:7], v[144:147], v[210:213], v[4:7]
	v_mfma_f32_16x16x32_bf16 v[8:11], v[136:139], v[210:213], v[8:11]
	s_barrier
	s_setprio 3
	v_mfma_f32_16x16x32_bf16 v[8:11], v[140:143], v[214:217], v[8:11]
	v_mfma_f32_16x16x32_bf16 v[12:15], v[132:135], v[214:217], v[12:15]
	v_mfma_f32_16x16x32_bf16 v[12:15], v[128:131], v[210:213], v[12:15]
	s_setprio 0
	s_add_i32 s57, s57, 2
	s_add_u32 s22, s22, 0x1000
	s_addc_u32 s23, s23, 0
	s_add_u32 s55, s55, 0x1000
	s_addc_u32 s56, s56, 0
	s_cmpk_gt_u32 s57, 0xfd
	s_cbranch_scc0 .LBB0_1625
